# plus: tail and GEMM1 LN-stat lane reductions via permlane swaps (no LDS round trips), adaLN GEMV with 63 loads in flight and b_ada preloaded
# baseline (speedup 1.0000x reference)
.LBB0_11:
	s_mul_i32 s6, s34, 24
	s_ashr_i32 s7, s6, 31
	v_lshl_add_u64 v[8:9], s[6:7], 2, v[4:5]
	v_mov_b32_e32 v47, v41
	s_mov_b32 s14, 0
	v_mov_b32_e32 v10, 0
	v_mov_b32_e32 v11, v3
	v_mov_b32_e32 v12, 0
	v_mov_b32_e32 v13, v3
	v_min_u32_e32 v80, 23, v67
	v_lshlrev_b32_e32 v80, 2, v80
	v_mov_b32_e32 v81, 0
	v_lshl_add_u64 v[254:255], s[6:7], 2, v[80:81]
	v_lshl_add_u64 v[254:255], s[54:55], 0, v[254:255]
	global_load_dword v252, v[254:255], off
	v_lshl_add_u64 v[82:83], s[6:7], 2, v[80:81]
	v_lshl_add_u64 v[82:83], s[52:53], 0, v[82:83]
	v_add_u32_e32 v84, -14, v41
	v_mul_u32_u24_e64 v84, v84, s33
	v_mov_b32_e32 v85, 0
	v_lshl_add_u64 v[82:83], v[84:85], 0, v[82:83]
	s_mov_b64 s[14:15], 0xc000
	v_add_u32_e32 v84, 0x12000, v35
	global_load_dword v86, v[82:83], off nt
	v_lshl_add_u64 v[82:83], v[82:83], 0, s[14:15]
	global_load_dword v87, v[82:83], off nt
	v_lshl_add_u64 v[82:83], v[82:83], 0, s[14:15]
	global_load_dword v88, v[82:83], off nt
	v_lshl_add_u64 v[82:83], v[82:83], 0, s[14:15]
	global_load_dword v89, v[82:83], off nt
	v_lshl_add_u64 v[82:83], v[82:83], 0, s[14:15]
	global_load_dword v90, v[82:83], off nt
	v_lshl_add_u64 v[82:83], v[82:83], 0, s[14:15]
	global_load_dword v91, v[82:83], off nt
	v_lshl_add_u64 v[82:83], v[82:83], 0, s[14:15]
	global_load_dword v92, v[82:83], off nt
	v_lshl_add_u64 v[82:83], v[82:83], 0, s[14:15]
	global_load_dword v93, v[82:83], off nt
	v_lshl_add_u64 v[82:83], v[82:83], 0, s[14:15]
	global_load_dword v94, v[82:83], off nt
	v_lshl_add_u64 v[82:83], v[82:83], 0, s[14:15]
	global_load_dword v95, v[82:83], off nt
	v_lshl_add_u64 v[82:83], v[82:83], 0, s[14:15]
	global_load_dword v96, v[82:83], off nt
	v_lshl_add_u64 v[82:83], v[82:83], 0, s[14:15]
	global_load_dword v97, v[82:83], off nt
	v_lshl_add_u64 v[82:83], v[82:83], 0, s[14:15]
	global_load_dword v98, v[82:83], off nt
	v_lshl_add_u64 v[82:83], v[82:83], 0, s[14:15]
	global_load_dword v99, v[82:83], off nt
	v_lshl_add_u64 v[82:83], v[82:83], 0, s[14:15]
	global_load_dword v100, v[82:83], off nt
	v_lshl_add_u64 v[82:83], v[82:83], 0, s[14:15]
	global_load_dword v101, v[82:83], off nt
	v_lshl_add_u64 v[82:83], v[82:83], 0, s[14:15]
	global_load_dword v102, v[82:83], off nt
	v_lshl_add_u64 v[82:83], v[82:83], 0, s[14:15]
	global_load_dword v103, v[82:83], off nt
	v_lshl_add_u64 v[82:83], v[82:83], 0, s[14:15]
	global_load_dword v104, v[82:83], off nt
	v_lshl_add_u64 v[82:83], v[82:83], 0, s[14:15]
	global_load_dword v105, v[82:83], off nt
	v_lshl_add_u64 v[82:83], v[82:83], 0, s[14:15]
	global_load_dword v106, v[82:83], off nt
	v_lshl_add_u64 v[82:83], v[82:83], 0, s[14:15]
	global_load_dword v107, v[82:83], off nt
	v_lshl_add_u64 v[82:83], v[82:83], 0, s[14:15]
	global_load_dword v108, v[82:83], off nt
	v_lshl_add_u64 v[82:83], v[82:83], 0, s[14:15]
	global_load_dword v109, v[82:83], off nt
	v_lshl_add_u64 v[82:83], v[82:83], 0, s[14:15]
	global_load_dword v110, v[82:83], off nt
	v_lshl_add_u64 v[82:83], v[82:83], 0, s[14:15]
	global_load_dword v111, v[82:83], off nt
	v_lshl_add_u64 v[82:83], v[82:83], 0, s[14:15]
	global_load_dword v112, v[82:83], off nt
	v_lshl_add_u64 v[82:83], v[82:83], 0, s[14:15]
	global_load_dword v113, v[82:83], off nt
	v_lshl_add_u64 v[82:83], v[82:83], 0, s[14:15]
	global_load_dword v114, v[82:83], off nt
	v_lshl_add_u64 v[82:83], v[82:83], 0, s[14:15]
	global_load_dword v115, v[82:83], off nt
	v_lshl_add_u64 v[82:83], v[82:83], 0, s[14:15]
	global_load_dword v116, v[82:83], off nt
	v_lshl_add_u64 v[82:83], v[82:83], 0, s[14:15]
	global_load_dword v117, v[82:83], off nt
	v_lshl_add_u64 v[82:83], v[82:83], 0, s[14:15]
	global_load_dword v118, v[82:83], off nt
	v_lshl_add_u64 v[82:83], v[82:83], 0, s[14:15]
	global_load_dword v119, v[82:83], off nt
	v_lshl_add_u64 v[82:83], v[82:83], 0, s[14:15]
	global_load_dword v120, v[82:83], off nt
	v_lshl_add_u64 v[82:83], v[82:83], 0, s[14:15]
	global_load_dword v121, v[82:83], off nt
	v_lshl_add_u64 v[82:83], v[82:83], 0, s[14:15]
	global_load_dword v122, v[82:83], off nt
	v_lshl_add_u64 v[82:83], v[82:83], 0, s[14:15]
	global_load_dword v123, v[82:83], off nt
	v_lshl_add_u64 v[82:83], v[82:83], 0, s[14:15]
	global_load_dword v124, v[82:83], off nt
	v_lshl_add_u64 v[82:83], v[82:83], 0, s[14:15]
	global_load_dword v125, v[82:83], off nt
	v_lshl_add_u64 v[82:83], v[82:83], 0, s[14:15]
	global_load_dword v126, v[82:83], off nt
	v_lshl_add_u64 v[82:83], v[82:83], 0, s[14:15]
	global_load_dword v127, v[82:83], off nt
	v_lshl_add_u64 v[82:83], v[82:83], 0, s[14:15]
	global_load_dword v128, v[82:83], off nt
	v_lshl_add_u64 v[82:83], v[82:83], 0, s[14:15]
	global_load_dword v129, v[82:83], off nt
	v_lshl_add_u64 v[82:83], v[82:83], 0, s[14:15]
	global_load_dword v130, v[82:83], off nt
	v_lshl_add_u64 v[82:83], v[82:83], 0, s[14:15]
	global_load_dword v131, v[82:83], off nt
	v_lshl_add_u64 v[82:83], v[82:83], 0, s[14:15]
	global_load_dword v132, v[82:83], off nt
	v_lshl_add_u64 v[82:83], v[82:83], 0, s[14:15]
	global_load_dword v133, v[82:83], off nt
	v_lshl_add_u64 v[82:83], v[82:83], 0, s[14:15]
	global_load_dword v134, v[82:83], off nt
	v_lshl_add_u64 v[82:83], v[82:83], 0, s[14:15]
	global_load_dword v135, v[82:83], off nt
	v_lshl_add_u64 v[82:83], v[82:83], 0, s[14:15]
	global_load_dword v136, v[82:83], off nt
	v_lshl_add_u64 v[82:83], v[82:83], 0, s[14:15]
	global_load_dword v137, v[82:83], off nt
	v_lshl_add_u64 v[82:83], v[82:83], 0, s[14:15]
	global_load_dword v138, v[82:83], off nt
	v_lshl_add_u64 v[82:83], v[82:83], 0, s[14:15]
	global_load_dword v139, v[82:83], off nt
	v_lshl_add_u64 v[82:83], v[82:83], 0, s[14:15]
	global_load_dword v140, v[82:83], off nt
	v_lshl_add_u64 v[82:83], v[82:83], 0, s[14:15]
	global_load_dword v141, v[82:83], off nt
	v_lshl_add_u64 v[82:83], v[82:83], 0, s[14:15]
	global_load_dword v142, v[82:83], off nt
	v_lshl_add_u64 v[82:83], v[82:83], 0, s[14:15]
	global_load_dword v143, v[82:83], off nt
	v_lshl_add_u64 v[82:83], v[82:83], 0, s[14:15]
	global_load_dword v144, v[82:83], off nt
	v_lshl_add_u64 v[82:83], v[82:83], 0, s[14:15]
	global_load_dword v145, v[82:83], off nt
	v_lshl_add_u64 v[82:83], v[82:83], 0, s[14:15]
	global_load_dword v146, v[82:83], off nt
	v_lshl_add_u64 v[82:83], v[82:83], 0, s[14:15]
	global_load_dword v147, v[82:83], off nt
	v_lshl_add_u64 v[82:83], v[82:83], 0, s[14:15]
	global_load_dword v148, v[82:83], off nt
	v_lshl_add_u64 v[82:83], v[82:83], 0, s[14:15]
	v_add_u32_e32 v85, 0, v84
	ds_read2st64_b32 v[150:151], v85 offset1:16
	ds_read2st64_b32 v[152:153], v85 offset0:32 offset1:48
	v_add_u32_e32 v85, 8, v84
	ds_read2st64_b32 v[154:155], v85 offset1:16
	ds_read2st64_b32 v[156:157], v85 offset0:32 offset1:48
	v_add_u32_e32 v85, 16, v84
	ds_read2st64_b32 v[158:159], v85 offset1:16
	ds_read2st64_b32 v[160:161], v85 offset0:32 offset1:48
	v_add_u32_e32 v85, 24, v84
	ds_read2st64_b32 v[162:163], v85 offset1:16
	ds_read2st64_b32 v[164:165], v85 offset0:32 offset1:48
	v_add_u32_e32 v85, 32, v84
	ds_read2st64_b32 v[166:167], v85 offset1:16
	ds_read2st64_b32 v[168:169], v85 offset0:32 offset1:48
	v_add_u32_e32 v85, 40, v84
	ds_read2st64_b32 v[170:171], v85 offset1:16
	ds_read2st64_b32 v[172:173], v85 offset0:32 offset1:48
	v_add_u32_e32 v85, 48, v84
	ds_read2st64_b32 v[174:175], v85 offset1:16
	ds_read2st64_b32 v[176:177], v85 offset0:32 offset1:48
	v_add_u32_e32 v85, 56, v84
	ds_read2st64_b32 v[178:179], v85 offset1:16
	ds_read2st64_b32 v[180:181], v85 offset0:32 offset1:48
	s_waitcnt lgkmcnt(0)
	v_add_u32_e32 v85, 64, v84
	ds_read2st64_b32 v[182:183], v85 offset1:16
	ds_read2st64_b32 v[184:185], v85 offset0:32 offset1:48
	v_add_u32_e32 v85, 72, v84
	ds_read2st64_b32 v[186:187], v85 offset1:16
	ds_read2st64_b32 v[188:189], v85 offset0:32 offset1:48
	v_add_u32_e32 v85, 80, v84
	ds_read2st64_b32 v[190:191], v85 offset1:16
	ds_read2st64_b32 v[192:193], v85 offset0:32 offset1:48
	v_add_u32_e32 v85, 88, v84
	ds_read2st64_b32 v[194:195], v85 offset1:16
	ds_read2st64_b32 v[196:197], v85 offset0:32 offset1:48
	v_add_u32_e32 v85, 96, v84
	ds_read2st64_b32 v[198:199], v85 offset1:16
	ds_read2st64_b32 v[200:201], v85 offset0:32 offset1:48
	v_add_u32_e32 v85, 104, v84
	ds_read2st64_b32 v[202:203], v85 offset1:16
	ds_read2st64_b32 v[204:205], v85 offset0:32 offset1:48
	v_add_u32_e32 v85, 112, v84
	ds_read2st64_b32 v[206:207], v85 offset1:16
	ds_read2st64_b32 v[208:209], v85 offset0:32 offset1:48
	v_add_u32_e32 v85, 120, v84
	ds_read2st64_b32 v[210:211], v85 offset1:16
	ds_read2st64_b32 v[212:213], v85 offset0:32 offset1:48
	s_waitcnt vmcnt(62)
	v_pk_fma_f32 v[10:11], v[86:87], v[150:151], v[10:11] op_sel_hi:[0,1,1]
	v_pk_fma_f32 v[12:13], v[86:87], v[152:153], v[12:13] op_sel_hi:[0,1,1]
	global_load_dword v149, v[82:83], off nt
	v_lshl_add_u64 v[82:83], v[82:83], 0, s[14:15]
	s_waitcnt vmcnt(62)
	v_pk_fma_f32 v[10:11], v[86:87], v[154:155], v[10:11] op_sel:[1,0,0] op_sel_hi:[1,1,1]
	v_pk_fma_f32 v[12:13], v[86:87], v[156:157], v[12:13] op_sel:[1,0,0] op_sel_hi:[1,1,1]
	s_waitcnt vmcnt(61)
	v_pk_fma_f32 v[10:11], v[88:89], v[158:159], v[10:11] op_sel_hi:[0,1,1]
	v_pk_fma_f32 v[12:13], v[88:89], v[160:161], v[12:13] op_sel_hi:[0,1,1]
	s_waitcnt vmcnt(60)
	v_pk_fma_f32 v[10:11], v[88:89], v[162:163], v[10:11] op_sel:[1,0,0] op_sel_hi:[1,1,1]
	v_pk_fma_f32 v[12:13], v[88:89], v[164:165], v[12:13] op_sel:[1,0,0] op_sel_hi:[1,1,1]
	s_waitcnt vmcnt(59)
	v_pk_fma_f32 v[10:11], v[90:91], v[166:167], v[10:11] op_sel_hi:[0,1,1]
	v_pk_fma_f32 v[12:13], v[90:91], v[168:169], v[12:13] op_sel_hi:[0,1,1]
	s_waitcnt vmcnt(58)
	v_pk_fma_f32 v[10:11], v[90:91], v[170:171], v[10:11] op_sel:[1,0,0] op_sel_hi:[1,1,1]
	v_pk_fma_f32 v[12:13], v[90:91], v[172:173], v[12:13] op_sel:[1,0,0] op_sel_hi:[1,1,1]
	s_waitcnt vmcnt(57)
	v_pk_fma_f32 v[10:11], v[92:93], v[174:175], v[10:11] op_sel_hi:[0,1,1]
	v_pk_fma_f32 v[12:13], v[92:93], v[176:177], v[12:13] op_sel_hi:[0,1,1]
	s_waitcnt vmcnt(56)
	v_pk_fma_f32 v[10:11], v[92:93], v[178:179], v[10:11] op_sel:[1,0,0] op_sel_hi:[1,1,1]
	v_pk_fma_f32 v[12:13], v[92:93], v[180:181], v[12:13] op_sel:[1,0,0] op_sel_hi:[1,1,1]
	s_waitcnt lgkmcnt(0)
	v_add_u32_e32 v85, 128, v84
	ds_read2st64_b32 v[150:151], v85 offset1:16
	ds_read2st64_b32 v[152:153], v85 offset0:32 offset1:48
	v_add_u32_e32 v85, 136, v84
	ds_read2st64_b32 v[154:155], v85 offset1:16
	ds_read2st64_b32 v[156:157], v85 offset0:32 offset1:48
	v_add_u32_e32 v85, 144, v84
	ds_read2st64_b32 v[158:159], v85 offset1:16
	ds_read2st64_b32 v[160:161], v85 offset0:32 offset1:48
	v_add_u32_e32 v85, 152, v84
	ds_read2st64_b32 v[162:163], v85 offset1:16
	ds_read2st64_b32 v[164:165], v85 offset0:32 offset1:48
	v_add_u32_e32 v85, 160, v84
	ds_read2st64_b32 v[166:167], v85 offset1:16
	ds_read2st64_b32 v[168:169], v85 offset0:32 offset1:48
	v_add_u32_e32 v85, 168, v84
	ds_read2st64_b32 v[170:171], v85 offset1:16
	ds_read2st64_b32 v[172:173], v85 offset0:32 offset1:48
	v_add_u32_e32 v85, 176, v84
	ds_read2st64_b32 v[174:175], v85 offset1:16
	ds_read2st64_b32 v[176:177], v85 offset0:32 offset1:48
	v_add_u32_e32 v85, 184, v84
	ds_read2st64_b32 v[178:179], v85 offset1:16
	ds_read2st64_b32 v[180:181], v85 offset0:32 offset1:48
	s_waitcnt vmcnt(55)
	v_pk_fma_f32 v[10:11], v[94:95], v[182:183], v[10:11] op_sel_hi:[0,1,1]
	v_pk_fma_f32 v[12:13], v[94:95], v[184:185], v[12:13] op_sel_hi:[0,1,1]
	s_waitcnt vmcnt(54)
	v_pk_fma_f32 v[10:11], v[94:95], v[186:187], v[10:11] op_sel:[1,0,0] op_sel_hi:[1,1,1]
	v_pk_fma_f32 v[12:13], v[94:95], v[188:189], v[12:13] op_sel:[1,0,0] op_sel_hi:[1,1,1]
	s_waitcnt vmcnt(53)
	v_pk_fma_f32 v[10:11], v[96:97], v[190:191], v[10:11] op_sel_hi:[0,1,1]
	v_pk_fma_f32 v[12:13], v[96:97], v[192:193], v[12:13] op_sel_hi:[0,1,1]
	s_waitcnt vmcnt(52)
	v_pk_fma_f32 v[10:11], v[96:97], v[194:195], v[10:11] op_sel:[1,0,0] op_sel_hi:[1,1,1]
	v_pk_fma_f32 v[12:13], v[96:97], v[196:197], v[12:13] op_sel:[1,0,0] op_sel_hi:[1,1,1]
	s_waitcnt vmcnt(51)
	v_pk_fma_f32 v[10:11], v[98:99], v[198:199], v[10:11] op_sel_hi:[0,1,1]
	v_pk_fma_f32 v[12:13], v[98:99], v[200:201], v[12:13] op_sel_hi:[0,1,1]
	s_waitcnt vmcnt(50)
	v_pk_fma_f32 v[10:11], v[98:99], v[202:203], v[10:11] op_sel:[1,0,0] op_sel_hi:[1,1,1]
	v_pk_fma_f32 v[12:13], v[98:99], v[204:205], v[12:13] op_sel:[1,0,0] op_sel_hi:[1,1,1]
	s_waitcnt vmcnt(49)
	v_pk_fma_f32 v[10:11], v[100:101], v[206:207], v[10:11] op_sel_hi:[0,1,1]
	v_pk_fma_f32 v[12:13], v[100:101], v[208:209], v[12:13] op_sel_hi:[0,1,1]
	s_waitcnt vmcnt(48)
	v_pk_fma_f32 v[10:11], v[100:101], v[210:211], v[10:11] op_sel:[1,0,0] op_sel_hi:[1,1,1]
	v_pk_fma_f32 v[12:13], v[100:101], v[212:213], v[12:13] op_sel:[1,0,0] op_sel_hi:[1,1,1]
	s_waitcnt lgkmcnt(0)
	v_add_u32_e32 v85, 192, v84
	ds_read2st64_b32 v[182:183], v85 offset1:16
	ds_read2st64_b32 v[184:185], v85 offset0:32 offset1:48
	v_add_u32_e32 v85, 200, v84
	ds_read2st64_b32 v[186:187], v85 offset1:16
	ds_read2st64_b32 v[188:189], v85 offset0:32 offset1:48
	v_add_u32_e32 v85, 208, v84
	ds_read2st64_b32 v[190:191], v85 offset1:16
	ds_read2st64_b32 v[192:193], v85 offset0:32 offset1:48
	v_add_u32_e32 v85, 216, v84
	ds_read2st64_b32 v[194:195], v85 offset1:16
	ds_read2st64_b32 v[196:197], v85 offset0:32 offset1:48
	v_add_u32_e32 v85, 224, v84
	ds_read2st64_b32 v[198:199], v85 offset1:16
	ds_read2st64_b32 v[200:201], v85 offset0:32 offset1:48
	v_add_u32_e32 v85, 232, v84
	ds_read2st64_b32 v[202:203], v85 offset1:16
	ds_read2st64_b32 v[204:205], v85 offset0:32 offset1:48
	v_add_u32_e32 v85, 240, v84
	ds_read2st64_b32 v[206:207], v85 offset1:16
	ds_read2st64_b32 v[208:209], v85 offset0:32 offset1:48
	v_add_u32_e32 v85, 248, v84
	ds_read2st64_b32 v[210:211], v85 offset1:16
	ds_read2st64_b32 v[212:213], v85 offset0:32 offset1:48
	s_waitcnt vmcnt(47)
	v_pk_fma_f32 v[10:11], v[102:103], v[150:151], v[10:11] op_sel_hi:[0,1,1]
	v_pk_fma_f32 v[12:13], v[102:103], v[152:153], v[12:13] op_sel_hi:[0,1,1]
	s_waitcnt vmcnt(46)
	v_pk_fma_f32 v[10:11], v[102:103], v[154:155], v[10:11] op_sel:[1,0,0] op_sel_hi:[1,1,1]
	v_pk_fma_f32 v[12:13], v[102:103], v[156:157], v[12:13] op_sel:[1,0,0] op_sel_hi:[1,1,1]
	s_waitcnt vmcnt(45)
	v_pk_fma_f32 v[10:11], v[104:105], v[158:159], v[10:11] op_sel_hi:[0,1,1]
	v_pk_fma_f32 v[12:13], v[104:105], v[160:161], v[12:13] op_sel_hi:[0,1,1]
	s_waitcnt vmcnt(44)
	v_pk_fma_f32 v[10:11], v[104:105], v[162:163], v[10:11] op_sel:[1,0,0] op_sel_hi:[1,1,1]
	v_pk_fma_f32 v[12:13], v[104:105], v[164:165], v[12:13] op_sel:[1,0,0] op_sel_hi:[1,1,1]
	s_waitcnt vmcnt(43)
	v_pk_fma_f32 v[10:11], v[106:107], v[166:167], v[10:11] op_sel_hi:[0,1,1]
	v_pk_fma_f32 v[12:13], v[106:107], v[168:169], v[12:13] op_sel_hi:[0,1,1]
	s_waitcnt vmcnt(42)
	v_pk_fma_f32 v[10:11], v[106:107], v[170:171], v[10:11] op_sel:[1,0,0] op_sel_hi:[1,1,1]
	v_pk_fma_f32 v[12:13], v[106:107], v[172:173], v[12:13] op_sel:[1,0,0] op_sel_hi:[1,1,1]
	s_waitcnt vmcnt(41)
	v_pk_fma_f32 v[10:11], v[108:109], v[174:175], v[10:11] op_sel_hi:[0,1,1]
	v_pk_fma_f32 v[12:13], v[108:109], v[176:177], v[12:13] op_sel_hi:[0,1,1]
	s_waitcnt vmcnt(40)
	v_pk_fma_f32 v[10:11], v[108:109], v[178:179], v[10:11] op_sel:[1,0,0] op_sel_hi:[1,1,1]
	v_pk_fma_f32 v[12:13], v[108:109], v[180:181], v[12:13] op_sel:[1,0,0] op_sel_hi:[1,1,1]
	s_waitcnt lgkmcnt(0)
	v_add_u32_e32 v85, 256, v84
	ds_read2st64_b32 v[150:151], v85 offset1:16
	ds_read2st64_b32 v[152:153], v85 offset0:32 offset1:48
	v_add_u32_e32 v85, 264, v84
	ds_read2st64_b32 v[154:155], v85 offset1:16
	ds_read2st64_b32 v[156:157], v85 offset0:32 offset1:48
	v_add_u32_e32 v85, 272, v84
	ds_read2st64_b32 v[158:159], v85 offset1:16
	ds_read2st64_b32 v[160:161], v85 offset0:32 offset1:48
	v_add_u32_e32 v85, 280, v84
	ds_read2st64_b32 v[162:163], v85 offset1:16
	ds_read2st64_b32 v[164:165], v85 offset0:32 offset1:48
	v_add_u32_e32 v85, 288, v84
	ds_read2st64_b32 v[166:167], v85 offset1:16
	ds_read2st64_b32 v[168:169], v85 offset0:32 offset1:48
	v_add_u32_e32 v85, 296, v84
	ds_read2st64_b32 v[170:171], v85 offset1:16
	ds_read2st64_b32 v[172:173], v85 offset0:32 offset1:48
	v_add_u32_e32 v85, 304, v84
	ds_read2st64_b32 v[174:175], v85 offset1:16
	ds_read2st64_b32 v[176:177], v85 offset0:32 offset1:48
	v_add_u32_e32 v85, 312, v84
	ds_read2st64_b32 v[178:179], v85 offset1:16
	ds_read2st64_b32 v[180:181], v85 offset0:32 offset1:48
	s_waitcnt vmcnt(39)
	v_pk_fma_f32 v[10:11], v[110:111], v[182:183], v[10:11] op_sel_hi:[0,1,1]
	v_pk_fma_f32 v[12:13], v[110:111], v[184:185], v[12:13] op_sel_hi:[0,1,1]
	s_waitcnt vmcnt(38)
	v_pk_fma_f32 v[10:11], v[110:111], v[186:187], v[10:11] op_sel:[1,0,0] op_sel_hi:[1,1,1]
	v_pk_fma_f32 v[12:13], v[110:111], v[188:189], v[12:13] op_sel:[1,0,0] op_sel_hi:[1,1,1]
	s_waitcnt vmcnt(37)
	v_pk_fma_f32 v[10:11], v[112:113], v[190:191], v[10:11] op_sel_hi:[0,1,1]
	v_pk_fma_f32 v[12:13], v[112:113], v[192:193], v[12:13] op_sel_hi:[0,1,1]
	s_waitcnt vmcnt(36)
	v_pk_fma_f32 v[10:11], v[112:113], v[194:195], v[10:11] op_sel:[1,0,0] op_sel_hi:[1,1,1]
	v_pk_fma_f32 v[12:13], v[112:113], v[196:197], v[12:13] op_sel:[1,0,0] op_sel_hi:[1,1,1]
	s_waitcnt vmcnt(35)
	v_pk_fma_f32 v[10:11], v[114:115], v[198:199], v[10:11] op_sel_hi:[0,1,1]
	v_pk_fma_f32 v[12:13], v[114:115], v[200:201], v[12:13] op_sel_hi:[0,1,1]
	s_waitcnt vmcnt(34)
	v_pk_fma_f32 v[10:11], v[114:115], v[202:203], v[10:11] op_sel:[1,0,0] op_sel_hi:[1,1,1]
	v_pk_fma_f32 v[12:13], v[114:115], v[204:205], v[12:13] op_sel:[1,0,0] op_sel_hi:[1,1,1]
	s_waitcnt vmcnt(33)
	v_pk_fma_f32 v[10:11], v[116:117], v[206:207], v[10:11] op_sel_hi:[0,1,1]
	v_pk_fma_f32 v[12:13], v[116:117], v[208:209], v[12:13] op_sel_hi:[0,1,1]
	s_waitcnt vmcnt(32)
	v_pk_fma_f32 v[10:11], v[116:117], v[210:211], v[10:11] op_sel:[1,0,0] op_sel_hi:[1,1,1]
	v_pk_fma_f32 v[12:13], v[116:117], v[212:213], v[12:13] op_sel:[1,0,0] op_sel_hi:[1,1,1]
	s_waitcnt lgkmcnt(0)
	v_add_u32_e32 v85, 320, v84
	ds_read2st64_b32 v[182:183], v85 offset1:16
	ds_read2st64_b32 v[184:185], v85 offset0:32 offset1:48
	v_add_u32_e32 v85, 328, v84
	ds_read2st64_b32 v[186:187], v85 offset1:16
	ds_read2st64_b32 v[188:189], v85 offset0:32 offset1:48
	v_add_u32_e32 v85, 336, v84
	ds_read2st64_b32 v[190:191], v85 offset1:16
	ds_read2st64_b32 v[192:193], v85 offset0:32 offset1:48
	v_add_u32_e32 v85, 344, v84
	ds_read2st64_b32 v[194:195], v85 offset1:16
	ds_read2st64_b32 v[196:197], v85 offset0:32 offset1:48
	v_add_u32_e32 v85, 352, v84
	ds_read2st64_b32 v[198:199], v85 offset1:16
	ds_read2st64_b32 v[200:201], v85 offset0:32 offset1:48
	v_add_u32_e32 v85, 360, v84
	ds_read2st64_b32 v[202:203], v85 offset1:16
	ds_read2st64_b32 v[204:205], v85 offset0:32 offset1:48
	v_add_u32_e32 v85, 368, v84
	ds_read2st64_b32 v[206:207], v85 offset1:16
	ds_read2st64_b32 v[208:209], v85 offset0:32 offset1:48
	v_add_u32_e32 v85, 376, v84
	ds_read2st64_b32 v[210:211], v85 offset1:16
	ds_read2st64_b32 v[212:213], v85 offset0:32 offset1:48
	s_waitcnt vmcnt(31)
	v_pk_fma_f32 v[10:11], v[118:119], v[150:151], v[10:11] op_sel_hi:[0,1,1]
	v_pk_fma_f32 v[12:13], v[118:119], v[152:153], v[12:13] op_sel_hi:[0,1,1]
	s_waitcnt vmcnt(30)
	v_pk_fma_f32 v[10:11], v[118:119], v[154:155], v[10:11] op_sel:[1,0,0] op_sel_hi:[1,1,1]
	v_pk_fma_f32 v[12:13], v[118:119], v[156:157], v[12:13] op_sel:[1,0,0] op_sel_hi:[1,1,1]
	s_waitcnt vmcnt(29)
	v_pk_fma_f32 v[10:11], v[120:121], v[158:159], v[10:11] op_sel_hi:[0,1,1]
	v_pk_fma_f32 v[12:13], v[120:121], v[160:161], v[12:13] op_sel_hi:[0,1,1]
	s_waitcnt vmcnt(28)
	v_pk_fma_f32 v[10:11], v[120:121], v[162:163], v[10:11] op_sel:[1,0,0] op_sel_hi:[1,1,1]
	v_pk_fma_f32 v[12:13], v[120:121], v[164:165], v[12:13] op_sel:[1,0,0] op_sel_hi:[1,1,1]
	s_waitcnt vmcnt(27)
	v_pk_fma_f32 v[10:11], v[122:123], v[166:167], v[10:11] op_sel_hi:[0,1,1]
	v_pk_fma_f32 v[12:13], v[122:123], v[168:169], v[12:13] op_sel_hi:[0,1,1]
	s_waitcnt vmcnt(26)
	v_pk_fma_f32 v[10:11], v[122:123], v[170:171], v[10:11] op_sel:[1,0,0] op_sel_hi:[1,1,1]
	v_pk_fma_f32 v[12:13], v[122:123], v[172:173], v[12:13] op_sel:[1,0,0] op_sel_hi:[1,1,1]
	s_waitcnt vmcnt(25)
	v_pk_fma_f32 v[10:11], v[124:125], v[174:175], v[10:11] op_sel_hi:[0,1,1]
	v_pk_fma_f32 v[12:13], v[124:125], v[176:177], v[12:13] op_sel_hi:[0,1,1]
	s_waitcnt vmcnt(24)
	v_pk_fma_f32 v[10:11], v[124:125], v[178:179], v[10:11] op_sel:[1,0,0] op_sel_hi:[1,1,1]
	v_pk_fma_f32 v[12:13], v[124:125], v[180:181], v[12:13] op_sel:[1,0,0] op_sel_hi:[1,1,1]
	s_waitcnt lgkmcnt(0)
	v_add_u32_e32 v85, 384, v84
	ds_read2st64_b32 v[150:151], v85 offset1:16
	ds_read2st64_b32 v[152:153], v85 offset0:32 offset1:48
	v_add_u32_e32 v85, 392, v84
	ds_read2st64_b32 v[154:155], v85 offset1:16
	ds_read2st64_b32 v[156:157], v85 offset0:32 offset1:48
	v_add_u32_e32 v85, 400, v84
	ds_read2st64_b32 v[158:159], v85 offset1:16
	ds_read2st64_b32 v[160:161], v85 offset0:32 offset1:48
	v_add_u32_e32 v85, 408, v84
	ds_read2st64_b32 v[162:163], v85 offset1:16
	ds_read2st64_b32 v[164:165], v85 offset0:32 offset1:48
	v_add_u32_e32 v85, 416, v84
	ds_read2st64_b32 v[166:167], v85 offset1:16
	ds_read2st64_b32 v[168:169], v85 offset0:32 offset1:48
	v_add_u32_e32 v85, 424, v84
	ds_read2st64_b32 v[170:171], v85 offset1:16
	ds_read2st64_b32 v[172:173], v85 offset0:32 offset1:48
	v_add_u32_e32 v85, 432, v84
	ds_read2st64_b32 v[174:175], v85 offset1:16
	ds_read2st64_b32 v[176:177], v85 offset0:32 offset1:48
	v_add_u32_e32 v85, 440, v84
	ds_read2st64_b32 v[178:179], v85 offset1:16
	ds_read2st64_b32 v[180:181], v85 offset0:32 offset1:48
	s_waitcnt vmcnt(23)
	v_pk_fma_f32 v[10:11], v[126:127], v[182:183], v[10:11] op_sel_hi:[0,1,1]
	v_pk_fma_f32 v[12:13], v[126:127], v[184:185], v[12:13] op_sel_hi:[0,1,1]
	s_waitcnt vmcnt(22)
	v_pk_fma_f32 v[10:11], v[126:127], v[186:187], v[10:11] op_sel:[1,0,0] op_sel_hi:[1,1,1]
	v_pk_fma_f32 v[12:13], v[126:127], v[188:189], v[12:13] op_sel:[1,0,0] op_sel_hi:[1,1,1]
	s_waitcnt vmcnt(21)
	v_pk_fma_f32 v[10:11], v[128:129], v[190:191], v[10:11] op_sel_hi:[0,1,1]
	v_pk_fma_f32 v[12:13], v[128:129], v[192:193], v[12:13] op_sel_hi:[0,1,1]
	s_waitcnt vmcnt(20)
	v_pk_fma_f32 v[10:11], v[128:129], v[194:195], v[10:11] op_sel:[1,0,0] op_sel_hi:[1,1,1]
	v_pk_fma_f32 v[12:13], v[128:129], v[196:197], v[12:13] op_sel:[1,0,0] op_sel_hi:[1,1,1]
	s_waitcnt vmcnt(19)
	v_pk_fma_f32 v[10:11], v[130:131], v[198:199], v[10:11] op_sel_hi:[0,1,1]
	v_pk_fma_f32 v[12:13], v[130:131], v[200:201], v[12:13] op_sel_hi:[0,1,1]
	s_waitcnt vmcnt(18)
	v_pk_fma_f32 v[10:11], v[130:131], v[202:203], v[10:11] op_sel:[1,0,0] op_sel_hi:[1,1,1]
	v_pk_fma_f32 v[12:13], v[130:131], v[204:205], v[12:13] op_sel:[1,0,0] op_sel_hi:[1,1,1]
	s_waitcnt vmcnt(17)
	v_pk_fma_f32 v[10:11], v[132:133], v[206:207], v[10:11] op_sel_hi:[0,1,1]
	v_pk_fma_f32 v[12:13], v[132:133], v[208:209], v[12:13] op_sel_hi:[0,1,1]
	s_waitcnt vmcnt(16)
	v_pk_fma_f32 v[10:11], v[132:133], v[210:211], v[10:11] op_sel:[1,0,0] op_sel_hi:[1,1,1]
	v_pk_fma_f32 v[12:13], v[132:133], v[212:213], v[12:13] op_sel:[1,0,0] op_sel_hi:[1,1,1]
	s_waitcnt lgkmcnt(0)
	v_add_u32_e32 v85, 448, v84
	ds_read2st64_b32 v[182:183], v85 offset1:16
	ds_read2st64_b32 v[184:185], v85 offset0:32 offset1:48
	v_add_u32_e32 v85, 456, v84
	ds_read2st64_b32 v[186:187], v85 offset1:16
	ds_read2st64_b32 v[188:189], v85 offset0:32 offset1:48
	v_add_u32_e32 v85, 464, v84
	ds_read2st64_b32 v[190:191], v85 offset1:16
	ds_read2st64_b32 v[192:193], v85 offset0:32 offset1:48
	v_add_u32_e32 v85, 472, v84
	ds_read2st64_b32 v[194:195], v85 offset1:16
	ds_read2st64_b32 v[196:197], v85 offset0:32 offset1:48
	v_add_u32_e32 v85, 480, v84
	ds_read2st64_b32 v[198:199], v85 offset1:16
	ds_read2st64_b32 v[200:201], v85 offset0:32 offset1:48
	v_add_u32_e32 v85, 488, v84
	ds_read2st64_b32 v[202:203], v85 offset1:16
	ds_read2st64_b32 v[204:205], v85 offset0:32 offset1:48
	v_add_u32_e32 v85, 496, v84
	ds_read2st64_b32 v[206:207], v85 offset1:16
	ds_read2st64_b32 v[208:209], v85 offset0:32 offset1:48
	v_add_u32_e32 v85, 504, v84
	ds_read2st64_b32 v[210:211], v85 offset1:16
	ds_read2st64_b32 v[212:213], v85 offset0:32 offset1:48
	s_waitcnt vmcnt(15)
	v_pk_fma_f32 v[10:11], v[134:135], v[150:151], v[10:11] op_sel_hi:[0,1,1]
	v_pk_fma_f32 v[12:13], v[134:135], v[152:153], v[12:13] op_sel_hi:[0,1,1]
	s_waitcnt vmcnt(14)
	v_pk_fma_f32 v[10:11], v[134:135], v[154:155], v[10:11] op_sel:[1,0,0] op_sel_hi:[1,1,1]
	v_pk_fma_f32 v[12:13], v[134:135], v[156:157], v[12:13] op_sel:[1,0,0] op_sel_hi:[1,1,1]
	s_waitcnt vmcnt(13)
	v_pk_fma_f32 v[10:11], v[136:137], v[158:159], v[10:11] op_sel_hi:[0,1,1]
	v_pk_fma_f32 v[12:13], v[136:137], v[160:161], v[12:13] op_sel_hi:[0,1,1]
	s_waitcnt vmcnt(12)
	v_pk_fma_f32 v[10:11], v[136:137], v[162:163], v[10:11] op_sel:[1,0,0] op_sel_hi:[1,1,1]
	v_pk_fma_f32 v[12:13], v[136:137], v[164:165], v[12:13] op_sel:[1,0,0] op_sel_hi:[1,1,1]
	s_waitcnt vmcnt(11)
	v_pk_fma_f32 v[10:11], v[138:139], v[166:167], v[10:11] op_sel_hi:[0,1,1]
	v_pk_fma_f32 v[12:13], v[138:139], v[168:169], v[12:13] op_sel_hi:[0,1,1]
	s_waitcnt vmcnt(10)
	v_pk_fma_f32 v[10:11], v[138:139], v[170:171], v[10:11] op_sel:[1,0,0] op_sel_hi:[1,1,1]
	v_pk_fma_f32 v[12:13], v[138:139], v[172:173], v[12:13] op_sel:[1,0,0] op_sel_hi:[1,1,1]
	s_waitcnt vmcnt(9)
	v_pk_fma_f32 v[10:11], v[140:141], v[174:175], v[10:11] op_sel_hi:[0,1,1]
	v_pk_fma_f32 v[12:13], v[140:141], v[176:177], v[12:13] op_sel_hi:[0,1,1]
	s_waitcnt vmcnt(8)
	v_pk_fma_f32 v[10:11], v[140:141], v[178:179], v[10:11] op_sel:[1,0,0] op_sel_hi:[1,1,1]
	v_pk_fma_f32 v[12:13], v[140:141], v[180:181], v[12:13] op_sel:[1,0,0] op_sel_hi:[1,1,1]
	s_waitcnt lgkmcnt(0)
	s_waitcnt vmcnt(7)
	v_pk_fma_f32 v[10:11], v[142:143], v[182:183], v[10:11] op_sel_hi:[0,1,1]
	v_pk_fma_f32 v[12:13], v[142:143], v[184:185], v[12:13] op_sel_hi:[0,1,1]
	s_waitcnt vmcnt(6)
	v_pk_fma_f32 v[10:11], v[142:143], v[186:187], v[10:11] op_sel:[1,0,0] op_sel_hi:[1,1,1]
	v_pk_fma_f32 v[12:13], v[142:143], v[188:189], v[12:13] op_sel:[1,0,0] op_sel_hi:[1,1,1]
	s_waitcnt vmcnt(5)
	v_pk_fma_f32 v[10:11], v[144:145], v[190:191], v[10:11] op_sel_hi:[0,1,1]
	v_pk_fma_f32 v[12:13], v[144:145], v[192:193], v[12:13] op_sel_hi:[0,1,1]
	s_waitcnt vmcnt(4)
	v_pk_fma_f32 v[10:11], v[144:145], v[194:195], v[10:11] op_sel:[1,0,0] op_sel_hi:[1,1,1]
	v_pk_fma_f32 v[12:13], v[144:145], v[196:197], v[12:13] op_sel:[1,0,0] op_sel_hi:[1,1,1]
	s_waitcnt vmcnt(3)
	v_pk_fma_f32 v[10:11], v[146:147], v[198:199], v[10:11] op_sel_hi:[0,1,1]
	v_pk_fma_f32 v[12:13], v[146:147], v[200:201], v[12:13] op_sel_hi:[0,1,1]
	s_waitcnt vmcnt(2)
	v_pk_fma_f32 v[10:11], v[146:147], v[202:203], v[10:11] op_sel:[1,0,0] op_sel_hi:[1,1,1]
	v_pk_fma_f32 v[12:13], v[146:147], v[204:205], v[12:13] op_sel:[1,0,0] op_sel_hi:[1,1,1]
	s_waitcnt vmcnt(1)
	v_pk_fma_f32 v[10:11], v[148:149], v[206:207], v[10:11] op_sel_hi:[0,1,1]
	v_pk_fma_f32 v[12:13], v[148:149], v[208:209], v[12:13] op_sel_hi:[0,1,1]
	s_waitcnt vmcnt(0)
	v_pk_fma_f32 v[10:11], v[148:149], v[210:211], v[10:11] op_sel:[1,0,0] op_sel_hi:[1,1,1]
	v_pk_fma_f32 v[12:13], v[148:149], v[212:213], v[12:13] op_sel:[1,0,0] op_sel_hi:[1,1,1]

.LBB0_31:
	s_or_b64 exec, exec, s[12:13]
	s_waitcnt lgkmcnt(0)
	s_barrier
	s_and_saveexec_b64 s[12:13], s[10:11]
	s_cbranch_execz .LBB0_33
	v_add_u32_e32 v8, s6, v67
	v_ashrrev_i32_e32 v9, 31, v8
	v_lshl_add_u64 v[8:9], v[8:9], 2, s[54:55]
	v_mov_b32_e32 v2, v252
	ds_read2st64_b32 v[8:9], v29 offset1:2
	ds_read2st64_b32 v[10:11], v29 offset0:4 offset1:6
	ds_read2st64_b32 v[12:13], v29 offset0:8 offset1:10
	ds_read2st64_b32 v[16:17], v29 offset0:12 offset1:14
	s_waitcnt vmcnt(0) lgkmcnt(3)
	v_add_f32_e32 v2, v2, v8
	v_add_f32_e32 v2, v2, v9
	s_waitcnt lgkmcnt(2)
	v_add_f32_e32 v2, v2, v10
	v_add_f32_e32 v2, v2, v11
	s_waitcnt lgkmcnt(1)
	v_add_f32_e32 v2, v2, v12
	v_add_f32_e32 v2, v2, v13
	s_waitcnt lgkmcnt(0)
	v_add_f32_e32 v2, v2, v16
	v_add_f32_e32 v2, v2, v17
	v_lshl_add_u64 v[8:9], s[6:7], 2, v[6:7]
	global_store_dword v[8:9], v2, off sc1

.LBB0_237:
	v_ashrrev_i32_e32 v141, 31, v140
	s_and_b64 vcc, exec, s[8:9]
	v_cvt_pk_bf16_f32 v130, v134, v135
	v_cvt_pk_bf16_f32 v131, v164, v165
	v_cvt_pk_bf16_f32 v132, v168, v169
	v_cvt_pk_bf16_f32 v133, v170, v171
	global_store_dwordx4 v[144:145], v[130:133], off offset:256
	s_cbranch_vccnz .LBB0_241
	s_nop 0
	v_and_b32_e32 v131, 64, v179
	v_xor_b32_e32 v130, 16, v179
	v_add_u32_e32 v132, 64, v131
	v_cmp_lt_i32_e32 vcc, v130, v132
	v_xor_b32_e32 v133, 32, v179
	s_nop 0
	v_cndmask_b32_e32 v130, v179, v130, vcc
	v_lshlrev_b32_e32 v131, 2, v130
	v_mov_b32_e32 v230, v142
	v_mov_b32_e32 v130, v142
	v_mov_b32_e32 v231, v143
	v_mov_b32_e32 v131, v143
	s_nop 1
	v_permlane16_swap_b32_e32 v230, v130
	v_permlane16_swap_b32_e32 v231, v131
	v_cmp_lt_i32_e32 vcc, v133, v132
	s_waitcnt lgkmcnt(0)
	v_pk_add_f32 v[130:131], v[142:143], v[130:131]
	v_cndmask_b32_e32 v132, v179, v133, vcc
	v_lshlrev_b32_e32 v133, 2, v132
	v_mov_b32_e32 v230, v130
	v_mov_b32_e32 v132, v130
	v_mov_b32_e32 v231, v131
	v_mov_b32_e32 v133, v131
	s_nop 1
	v_permlane32_swap_b32_e32 v230, v132
	v_permlane32_swap_b32_e32 v231, v133
	s_and_saveexec_b64 s[10:11], s[12:13]
	s_cbranch_execz .LBB0_240
	s_lshl_b32 s40, s20, 2
	s_waitcnt lgkmcnt(0)
	v_pk_add_f32 v[130:131], v[130:131], v[132:133]
	v_lshlrev_b64 v[132:133], 4, v[140:141]
	s_add_i32 s40, s40, -16
	v_or_b32_e32 v132, s40, v132
	v_or_b32_e32 v132, s55, v132
	v_lshl_add_u64 v[132:133], v[132:133], 3, s[80:81]
	global_store_dwordx2 v[132:133], v[130:131], off

.LBB0_270:
	s_and_b64 vcc, exec, s[8:9]
	v_cvt_pk_bf16_f32 v114, v118, v119
	v_cvt_pk_bf16_f32 v115, v128, v129
	v_cvt_pk_bf16_f32 v116, v132, v133
	v_cvt_pk_bf16_f32 v117, v134, v135
	global_store_dwordx4 v[126:127], v[114:117], off offset:256
	s_cbranch_vccnz .LBB0_274
	s_nop 0
	v_and_b32_e32 v115, 64, v179
	v_xor_b32_e32 v114, 16, v179
	v_add_u32_e32 v116, 64, v115
	v_cmp_lt_i32_e32 vcc, v114, v116
	v_xor_b32_e32 v117, 32, v179
	s_nop 0
	v_cndmask_b32_e32 v114, v179, v114, vcc
	v_lshlrev_b32_e32 v115, 2, v114
	v_mov_b32_e32 v230, v124
	v_mov_b32_e32 v114, v124
	v_mov_b32_e32 v231, v125
	v_mov_b32_e32 v115, v125
	s_nop 1
	v_permlane16_swap_b32_e32 v230, v114
	v_permlane16_swap_b32_e32 v231, v115
	v_cmp_lt_i32_e32 vcc, v117, v116
	s_waitcnt lgkmcnt(0)
	v_pk_add_f32 v[114:115], v[124:125], v[114:115]
	v_cndmask_b32_e32 v116, v179, v117, vcc
	v_lshlrev_b32_e32 v117, 2, v116
	v_mov_b32_e32 v230, v114
	v_mov_b32_e32 v116, v114
	v_mov_b32_e32 v231, v115
	v_mov_b32_e32 v117, v115
	s_nop 1
	v_permlane32_swap_b32_e32 v230, v116
	v_permlane32_swap_b32_e32 v231, v117
	s_and_saveexec_b64 s[0:1], s[12:13]
	s_cbranch_execz .LBB0_273
	v_ashrrev_i32_e32 v123, 31, v122
	s_lshl_b32 s40, s20, 2
	s_waitcnt lgkmcnt(0)
	v_pk_add_f32 v[114:115], v[114:115], v[116:117]
	v_lshlrev_b64 v[116:117], 4, v[122:123]
	s_add_i32 s40, s40, -16
	v_or_b32_e32 v116, s40, v116
	v_or_b32_e32 v116, s55, v116
	v_lshl_add_u64 v[116:117], v[116:117], 3, s[80:81]
	global_store_dwordx2 v[116:117], v[114:115], off

.LBB0_303:
	s_and_b64 vcc, exec, s[8:9]
	v_cvt_pk_bf16_f32 v98, v102, v103
	v_cvt_pk_bf16_f32 v99, v112, v113
	v_cvt_pk_bf16_f32 v100, v116, v117
	v_cvt_pk_bf16_f32 v101, v118, v119
	global_store_dwordx4 v[110:111], v[98:101], off offset:256
	s_cbranch_vccnz .LBB0_307
	s_nop 0
	v_and_b32_e32 v99, 64, v179
	v_xor_b32_e32 v98, 16, v179
	v_add_u32_e32 v100, 64, v99
	v_cmp_lt_i32_e32 vcc, v98, v100
	v_xor_b32_e32 v101, 32, v179
	s_nop 0
	v_cndmask_b32_e32 v98, v179, v98, vcc
	v_lshlrev_b32_e32 v99, 2, v98
	v_mov_b32_e32 v230, v108
	v_mov_b32_e32 v98, v108
	v_mov_b32_e32 v231, v109
	v_mov_b32_e32 v99, v109
	s_nop 1
	v_permlane16_swap_b32_e32 v230, v98
	v_permlane16_swap_b32_e32 v231, v99
	v_cmp_lt_i32_e32 vcc, v101, v100
	s_waitcnt lgkmcnt(0)
	v_pk_add_f32 v[98:99], v[108:109], v[98:99]
	v_cndmask_b32_e32 v100, v179, v101, vcc
	v_lshlrev_b32_e32 v101, 2, v100
	v_mov_b32_e32 v230, v98
	v_mov_b32_e32 v100, v98
	v_mov_b32_e32 v231, v99
	v_mov_b32_e32 v101, v99
	s_nop 1
	v_permlane32_swap_b32_e32 v230, v100
	v_permlane32_swap_b32_e32 v231, v101
	s_and_saveexec_b64 s[0:1], s[12:13]
	s_cbranch_execz .LBB0_306
	v_ashrrev_i32_e32 v107, 31, v106
	s_lshl_b32 s40, s20, 2
	s_waitcnt lgkmcnt(0)
	v_pk_add_f32 v[98:99], v[98:99], v[100:101]
	v_lshlrev_b64 v[100:101], 4, v[106:107]
	s_add_i32 s40, s40, -16
	v_or_b32_e32 v100, s40, v100
	v_or_b32_e32 v100, s55, v100
	v_lshl_add_u64 v[100:101], v[100:101], 3, s[80:81]
	global_store_dwordx2 v[100:101], v[98:99], off

.LBB0_336:
	s_and_b64 vcc, exec, s[8:9]
	v_cvt_pk_bf16_f32 v82, v86, v87
	v_cvt_pk_bf16_f32 v83, v96, v97
	v_cvt_pk_bf16_f32 v84, v100, v101
	v_cvt_pk_bf16_f32 v85, v102, v103
	global_store_dwordx4 v[94:95], v[82:85], off offset:256
	s_cbranch_vccnz .LBB0_340
	s_nop 0
	v_and_b32_e32 v83, 64, v179
	v_xor_b32_e32 v82, 16, v179
	v_add_u32_e32 v84, 64, v83
	v_cmp_lt_i32_e32 vcc, v82, v84
	v_xor_b32_e32 v85, 32, v179
	s_nop 0
	v_cndmask_b32_e32 v82, v179, v82, vcc
	v_lshlrev_b32_e32 v83, 2, v82
	v_mov_b32_e32 v230, v92
	v_mov_b32_e32 v82, v92
	v_mov_b32_e32 v231, v93
	v_mov_b32_e32 v83, v93
	s_nop 1
	v_permlane16_swap_b32_e32 v230, v82
	v_permlane16_swap_b32_e32 v231, v83
	v_cmp_lt_i32_e32 vcc, v85, v84
	s_waitcnt lgkmcnt(0)
	v_pk_add_f32 v[82:83], v[92:93], v[82:83]
	v_cndmask_b32_e32 v84, v179, v85, vcc
	v_lshlrev_b32_e32 v85, 2, v84
	v_mov_b32_e32 v230, v82
	v_mov_b32_e32 v84, v82
	v_mov_b32_e32 v231, v83
	v_mov_b32_e32 v85, v83
	s_nop 1
	v_permlane32_swap_b32_e32 v230, v84
	v_permlane32_swap_b32_e32 v231, v85
	s_and_saveexec_b64 s[0:1], s[12:13]
	s_cbranch_execz .LBB0_339
	v_ashrrev_i32_e32 v91, 31, v90
	s_lshl_b32 s40, s20, 2
	s_waitcnt lgkmcnt(0)
	v_pk_add_f32 v[82:83], v[82:83], v[84:85]
	v_lshlrev_b64 v[84:85], 4, v[90:91]
	s_add_i32 s40, s40, -16
	v_or_b32_e32 v84, s40, v84
	v_or_b32_e32 v84, s55, v84
	v_lshl_add_u64 v[84:85], v[84:85], 3, s[80:81]
	global_store_dwordx2 v[84:85], v[82:83], off

.LBB0_369:
	s_and_b64 vcc, exec, s[8:9]
	v_cvt_pk_bf16_f32 v66, v70, v71
	v_cvt_pk_bf16_f32 v67, v80, v81
	v_cvt_pk_bf16_f32 v68, v84, v85
	v_cvt_pk_bf16_f32 v69, v86, v87
	global_store_dwordx4 v[78:79], v[66:69], off offset:256
	s_cbranch_vccnz .LBB0_373
	s_nop 0
	v_and_b32_e32 v67, 64, v179
	v_xor_b32_e32 v66, 16, v179
	v_add_u32_e32 v68, 64, v67
	v_cmp_lt_i32_e32 vcc, v66, v68
	v_xor_b32_e32 v69, 32, v179
	s_nop 0
	v_cndmask_b32_e32 v66, v179, v66, vcc
	v_lshlrev_b32_e32 v67, 2, v66
	v_mov_b32_e32 v230, v76
	v_mov_b32_e32 v66, v76
	v_mov_b32_e32 v231, v77
	v_mov_b32_e32 v67, v77
	s_nop 1
	v_permlane16_swap_b32_e32 v230, v66
	v_permlane16_swap_b32_e32 v231, v67
	v_cmp_lt_i32_e32 vcc, v69, v68
	s_waitcnt lgkmcnt(0)
	v_pk_add_f32 v[66:67], v[76:77], v[66:67]
	v_cndmask_b32_e32 v68, v179, v69, vcc
	v_lshlrev_b32_e32 v69, 2, v68
	v_mov_b32_e32 v230, v66
	v_mov_b32_e32 v68, v66
	v_mov_b32_e32 v231, v67
	v_mov_b32_e32 v69, v67
	s_nop 1
	v_permlane32_swap_b32_e32 v230, v68
	v_permlane32_swap_b32_e32 v231, v69
	s_and_saveexec_b64 s[0:1], s[12:13]
	s_cbranch_execz .LBB0_372
	v_ashrrev_i32_e32 v75, 31, v74
	s_lshl_b32 s40, s20, 2
	s_waitcnt lgkmcnt(0)
	v_pk_add_f32 v[66:67], v[66:67], v[68:69]
	v_lshlrev_b64 v[68:69], 4, v[74:75]
	s_add_i32 s40, s40, -16
	v_or_b32_e32 v68, s40, v68
	v_or_b32_e32 v68, s55, v68
	v_lshl_add_u64 v[68:69], v[68:69], 3, s[80:81]
	global_store_dwordx2 v[68:69], v[66:67], off

.LBB0_402:
	s_and_b64 vcc, exec, s[8:9]
	v_cvt_pk_bf16_f32 v50, v54, v55
	v_cvt_pk_bf16_f32 v51, v64, v65
	v_cvt_pk_bf16_f32 v52, v68, v69
	v_cvt_pk_bf16_f32 v53, v70, v71
	global_store_dwordx4 v[62:63], v[50:53], off offset:256
	s_cbranch_vccnz .LBB0_406
	s_nop 0
	v_and_b32_e32 v51, 64, v179
	v_xor_b32_e32 v50, 16, v179
	v_add_u32_e32 v52, 64, v51
	v_cmp_lt_i32_e32 vcc, v50, v52
	v_xor_b32_e32 v53, 32, v179
	s_nop 0
	v_cndmask_b32_e32 v50, v179, v50, vcc
	v_lshlrev_b32_e32 v51, 2, v50
	v_mov_b32_e32 v230, v60
	v_mov_b32_e32 v50, v60
	v_mov_b32_e32 v231, v61
	v_mov_b32_e32 v51, v61
	s_nop 1
	v_permlane16_swap_b32_e32 v230, v50
	v_permlane16_swap_b32_e32 v231, v51
	v_cmp_lt_i32_e32 vcc, v53, v52
	s_waitcnt lgkmcnt(0)
	v_pk_add_f32 v[50:51], v[60:61], v[50:51]
	v_cndmask_b32_e32 v52, v179, v53, vcc
	v_lshlrev_b32_e32 v53, 2, v52
	v_mov_b32_e32 v230, v50
	v_mov_b32_e32 v52, v50
	v_mov_b32_e32 v231, v51
	v_mov_b32_e32 v53, v51
	s_nop 1
	v_permlane32_swap_b32_e32 v230, v52
	v_permlane32_swap_b32_e32 v231, v53
	s_and_saveexec_b64 s[0:1], s[12:13]
	s_cbranch_execz .LBB0_405
	v_ashrrev_i32_e32 v59, 31, v58
	s_lshl_b32 s40, s20, 2
	s_waitcnt lgkmcnt(0)
	v_pk_add_f32 v[50:51], v[50:51], v[52:53]
	v_lshlrev_b64 v[52:53], 4, v[58:59]
	s_add_i32 s40, s40, -16
	v_or_b32_e32 v52, s40, v52
	v_or_b32_e32 v52, s55, v52
	v_lshl_add_u64 v[52:53], v[52:53], 3, s[80:81]
	global_store_dwordx2 v[52:53], v[50:51], off

.LBB0_435:
	s_and_b64 vcc, exec, s[8:9]
	v_cvt_pk_bf16_f32 v26, v30, v31
	v_cvt_pk_bf16_f32 v27, v48, v49
	v_cvt_pk_bf16_f32 v28, v52, v53
	v_cvt_pk_bf16_f32 v29, v54, v55
	global_store_dwordx4 v[46:47], v[26:29], off offset:256
	s_cbranch_vccnz .LBB0_439
	s_nop 0
	v_and_b32_e32 v27, 64, v179
	v_xor_b32_e32 v26, 16, v179
	v_add_u32_e32 v28, 64, v27
	v_cmp_lt_i32_e32 vcc, v26, v28
	v_xor_b32_e32 v29, 32, v179
	s_nop 0
	v_cndmask_b32_e32 v26, v179, v26, vcc
	v_lshlrev_b32_e32 v27, 2, v26
	v_mov_b32_e32 v230, v44
	v_mov_b32_e32 v26, v44
	v_mov_b32_e32 v231, v45
	v_mov_b32_e32 v27, v45
	s_nop 1
	v_permlane16_swap_b32_e32 v230, v26
	v_permlane16_swap_b32_e32 v231, v27
	v_cmp_lt_i32_e32 vcc, v29, v28
	s_waitcnt lgkmcnt(0)
	v_pk_add_f32 v[26:27], v[44:45], v[26:27]
	v_cndmask_b32_e32 v28, v179, v29, vcc
	v_lshlrev_b32_e32 v29, 2, v28
	v_mov_b32_e32 v230, v26
	v_mov_b32_e32 v28, v26
	v_mov_b32_e32 v231, v27
	v_mov_b32_e32 v29, v27
	s_nop 1
	v_permlane32_swap_b32_e32 v230, v28
	v_permlane32_swap_b32_e32 v231, v29
	s_and_saveexec_b64 s[0:1], s[12:13]
	s_cbranch_execz .LBB0_438
	v_ashrrev_i32_e32 v43, 31, v42
	s_lshl_b32 s40, s20, 2
	s_waitcnt lgkmcnt(0)
	v_pk_add_f32 v[26:27], v[26:27], v[28:29]
	v_lshlrev_b64 v[28:29], 4, v[42:43]
	s_add_i32 s40, s40, -16
	v_or_b32_e32 v28, s40, v28
	v_or_b32_e32 v28, s55, v28
	v_lshl_add_u64 v[28:29], v[28:29], 3, s[80:81]
	global_store_dwordx2 v[28:29], v[26:27], off

.LBB0_468:
	s_and_b64 vcc, exec, s[8:9]
	v_cvt_pk_bf16_f32 v2, v6, v7
	v_cvt_pk_bf16_f32 v3, v18, v19
	v_cvt_pk_bf16_f32 v4, v20, v21
	v_cvt_pk_bf16_f32 v5, v22, v23
	global_store_dwordx4 v[16:17], v[2:5], off offset:256
	s_cbranch_vccnz .LBB0_472
	s_nop 0
	v_and_b32_e32 v3, 64, v179
	v_xor_b32_e32 v2, 16, v179
	v_add_u32_e32 v4, 64, v3
	v_cmp_lt_i32_e32 vcc, v2, v4
	v_xor_b32_e32 v5, 32, v179
	s_nop 0
	v_cndmask_b32_e32 v2, v179, v2, vcc
	v_lshlrev_b32_e32 v3, 2, v2
	v_mov_b32_e32 v230, v12
	v_mov_b32_e32 v2, v12
	v_mov_b32_e32 v231, v13
	v_mov_b32_e32 v3, v13
	s_nop 1
	v_permlane16_swap_b32_e32 v230, v2
	v_permlane16_swap_b32_e32 v231, v3
	v_cmp_lt_i32_e32 vcc, v5, v4
	s_waitcnt lgkmcnt(0)
	v_pk_add_f32 v[2:3], v[12:13], v[2:3]
	v_cndmask_b32_e32 v4, v179, v5, vcc
	v_lshlrev_b32_e32 v5, 2, v4
	v_mov_b32_e32 v230, v2
	v_mov_b32_e32 v4, v2
	v_mov_b32_e32 v231, v3
	v_mov_b32_e32 v5, v3
	s_nop 1
	v_permlane32_swap_b32_e32 v230, v4
	v_permlane32_swap_b32_e32 v231, v5
	s_and_saveexec_b64 s[0:1], s[12:13]
	s_cbranch_execz .LBB0_471
	v_ashrrev_i32_e32 v11, 31, v10
	s_lshl_b32 s6, s20, 2
	s_waitcnt lgkmcnt(0)
	v_pk_add_f32 v[2:3], v[2:3], v[4:5]
	v_lshlrev_b64 v[4:5], 4, v[10:11]
	s_add_i32 s6, s6, -16
	v_or_b32_e32 v4, s6, v4
	v_or_b32_e32 v4, s55, v4
	v_lshl_add_u64 v[4:5], v[4:5], 3, s[80:81]
	global_store_dwordx2 v[4:5], v[2:3], off

.LBB0_1462:
	s_lshl_b32 s23, s48, 8
	v_add_u32_e32 v160, s23, v180
	s_lshr_b32 s4, s48, 4
	v_ashrrev_i32_e32 v161, 31, v160
	s_mulk_i32 s4, 0x1800
	v_lshl_or_b32 v158, s22, 8, v182
	v_lshlrev_b64 v[96:97], 11, v[160:161]
	s_ashr_i32 s5, s4, 31
	v_ashrrev_i32_e32 v159, 31, v158
	v_lshl_add_u64 v[96:97], s[74:75], 0, v[96:97]
	s_lshl_b64 s[4:5], s[4:5], 2
	v_lshl_add_u64 v[96:97], v[158:159], 1, v[96:97]
	s_add_u32 s4, s86, s4
	v_mov_b32_e32 v190, v218
	v_lshl_add_u64 v[96:97], v[96:97], 0, v[148:149]
	s_addc_u32 s5, s87, s5
	global_load_dwordx4 v[162:165], v[96:97], off
	global_load_dwordx4 v[166:169], v[96:97], off offset:256
	v_mov_b64_e32 v[226:227], v[96:97]
	v_lshl_add_u64 v[96:97], v[158:159], 2, s[4:5]
	v_add_co_u32_e32 v98, vcc, s45, v96
	v_and_b32_e32 v171, 64, v187
	s_nop 0
	v_addc_co_u32_e32 v99, vcc, 0, v97, vcc
	global_load_dwordx4 v[104:107], v[98:99], off
	v_lshl_add_u64 v[96:97], v[96:97], 0, s[16:17]
	global_load_dwordx4 v[108:111], v[96:97], off offset:64
	global_load_dwordx4 v[100:103], v[96:97], off offset:512
	s_nop 0
	global_load_dwordx4 v[96:99], v[96:97], off offset:576
	v_add_co_u32_e32 v228, vcc, 0x8000, v226
	s_nop 1
	v_addc_co_u32_e32 v229, vcc, 0, v227, vcc
	global_load_dwordx4 v[232:235], v[228:229], off offset:256
	global_load_dwordx4 v[228:231], v[228:229], off
	v_add_co_u32_e32 v236, vcc, 0x10000, v226
	s_nop 1
	v_addc_co_u32_e32 v237, vcc, 0, v227, vcc
	global_load_dwordx4 v[240:243], v[236:237], off offset:256
	global_load_dwordx4 v[236:239], v[236:237], off
	v_add_co_u32_e32 v244, vcc, 0x18000, v226
	s_nop 1
	v_addc_co_u32_e32 v245, vcc, 0, v227, vcc
	global_load_dwordx4 v[248:251], v[244:245], off offset:256
	global_load_dwordx4 v[244:247], v[244:245], off
	v_add_co_u32_e32 v252, vcc, 0x40000, v226
	s_nop 1
	v_addc_co_u32_e32 v253, vcc, 0, v227, vcc
	global_load_dwordx4 v[144:147], v[252:253], off offset:256
	global_load_dwordx4 v[252:255], v[252:253], off
	v_add_co_u32_e32 v150, vcc, 0x48000, v226
	s_nop 1
	v_addc_co_u32_e32 v151, vcc, 0, v227, vcc
	global_load_dwordx4 v[154:157], v[150:151], off offset:256
	global_load_dwordx4 v[150:153], v[150:151], off
	v_add_co_u32_e32 v210, vcc, 0x50000, v226
	s_nop 1
	v_addc_co_u32_e32 v211, vcc, 0, v227, vcc
	global_load_dwordx4 v[214:217], v[210:211], off offset:256
	global_load_dwordx4 v[210:213], v[210:211], off
	v_add_co_u32_e32 v220, vcc, 0x58000, v226
	s_nop 1
	v_addc_co_u32_e32 v221, vcc, 0, v227, vcc
	global_load_dwordx4 v[224:227], v[220:221], off offset:256
	global_load_dwordx4 v[220:223], v[220:221], off
	v_xor_b32_e32 v170, 16, v187
	v_add_u32_e32 v178, 64, v171
	v_cmp_lt_i32_e32 vcc, v170, v178
	s_waitcnt vmcnt(14)
	v_mov_b32_e32 v171, v165
	v_cndmask_b32_e32 v170, v187, v170, vcc
	v_lshlrev_b32_e32 v191, 2, v170
	v_mov_b32_e32 v170, v164
	v_mov_b32_e32 v175, v168
	v_mov_b32_e32 v177, v169
	v_permlane16_swap_b32_e32 v162, v170
	v_permlane16_swap_b32_e32 v163, v171
	v_permlane16_swap_b32_e32 v166, v175
	v_permlane16_swap_b32_e32 v167, v177
	v_lshlrev_b32_e32 v164, 16, v162
	v_and_b32_e32 v165, 0xffff0000, v162
	v_lshlrev_b32_e32 v162, 16, v163
	v_and_b32_e32 v163, 0xffff0000, v163
	v_lshlrev_b32_e32 v168, 16, v170
	v_and_b32_e32 v169, 0xffff0000, v170
	v_lshlrev_b32_e32 v170, 16, v171
	v_and_b32_e32 v171, 0xffff0000, v171
	v_lshlrev_b32_e32 v172, 16, v166
	v_and_b32_e32 v173, 0xffff0000, v166
	v_lshlrev_b32_e32 v166, 16, v167
	v_and_b32_e32 v167, 0xffff0000, v167
	v_pk_fma_f32 v[142:143], v[142:143], v[106:107], v[162:163]
	v_pk_fma_f32 v[140:141], v[140:141], v[104:105], v[164:165]
	v_pk_fma_f32 v[138:139], v[138:139], v[110:111], v[170:171]
	v_pk_fma_f32 v[136:137], v[136:137], v[108:109], v[168:169]
	v_lshlrev_b32_e32 v174, 16, v175
	v_and_b32_e32 v175, 0xffff0000, v175
	v_lshlrev_b32_e32 v176, 16, v177
	v_and_b32_e32 v177, 0xffff0000, v177
	v_pk_fma_f32 v[134:135], v[134:135], v[102:103], v[166:167]
	v_pk_fma_f32 v[132:133], v[132:133], v[100:101], v[172:173]
	v_mul_f32_e32 v162, v141, v141
	v_mul_f32_e32 v163, v143, v143
	v_mul_f32_e32 v164, v137, v137
	v_mul_f32_e32 v165, v139, v139
	v_pk_fma_f32 v[130:131], v[130:131], v[98:99], v[176:177]
	v_pk_fma_f32 v[128:129], v[128:129], v[96:97], v[174:175]
	v_mul_f32_e32 v166, v133, v133
	v_mul_f32_e32 v167, v135, v135
	v_fmac_f32_e32 v162, v140, v140
	v_fmac_f32_e32 v163, v142, v142
	v_fmac_f32_e32 v164, v136, v136
	v_fmac_f32_e32 v165, v138, v138
	v_mul_f32_e32 v168, v129, v129
	v_mul_f32_e32 v169, v131, v131
	v_fmac_f32_e32 v166, v132, v132
	v_fmac_f32_e32 v167, v134, v134
	v_add_f32_e32 v162, v162, v163
	v_add_f32_e32 v163, v164, v165
	v_fmac_f32_e32 v168, v128, v128
	v_fmac_f32_e32 v169, v130, v130
	v_add_f32_e32 v164, v166, v167
	v_add_f32_e32 v162, v162, v163
	v_add_f32_e32 v162, v162, v164
	v_add_f32_e32 v163, v168, v169
	v_add_f32_e32 v162, v163, v162
	v_mov_b32_e32 v219, v162
	v_mov_b32_e32 v163, v162
	s_nop 1
	v_permlane16_swap_b32_e32 v219, v163
	v_xor_b32_e32 v164, 32, v187
	v_cmp_lt_i32_e32 vcc, v164, v178
	s_waitcnt lgkmcnt(0)
	v_add_f32_e32 v162, v162, v163
	v_cndmask_b32_e32 v164, v187, v164, vcc
	v_lshlrev_b32_e32 v192, 2, v164
	v_mov_b32_e32 v219, v162
	v_mov_b32_e32 v163, v162
	s_nop 1
	v_permlane32_swap_b32_e32 v219, v163
	s_and_saveexec_b64 s[4:5], s[0:1]
	s_cbranch_execz .LBB0_1464
	s_waitcnt lgkmcnt(0)
	v_add_f32_e32 v162, v162, v163
	ds_write_b32 v189, v162
.LBB0_1464:
	s_or_b64 exec, exec, s[4:5]
	v_or_b32_e32 v162, 16, v160
	s_waitcnt lgkmcnt(0)
	v_ashrrev_i32_e32 v163, 31, v162
	v_lshlrev_b64 v[164:165], 11, v[162:163]
	v_lshl_add_u64 v[164:165], s[74:75], 0, v[164:165]
	v_lshl_add_u64 v[164:165], v[158:159], 1, v[164:165]
	v_lshl_add_u64 v[168:169], v[164:165], 0, v[148:149]
	s_waitcnt vmcnt(12)
	v_mov_b64_e32 v[164:165], v[228:229]
	v_mov_b64_e32 v[166:167], v[230:231]
	s_nop 0
	v_mov_b64_e32 v[168:169], v[232:233]
	v_mov_b64_e32 v[170:171], v[234:235]
	s_nop 0
	v_mov_b32_e32 v172, v166
	v_mov_b32_e32 v173, v167
	s_nop 0
	v_mov_b32_e32 v177, v170
	v_mov_b32_e32 v179, v171
	v_permlane16_swap_b32_e32 v164, v172
	v_permlane16_swap_b32_e32 v165, v173
	v_permlane16_swap_b32_e32 v168, v177
	v_permlane16_swap_b32_e32 v169, v179
	v_lshlrev_b32_e32 v166, 16, v164
	v_and_b32_e32 v167, 0xffff0000, v164
	v_lshlrev_b32_e32 v164, 16, v165
	v_and_b32_e32 v165, 0xffff0000, v165
	v_lshlrev_b32_e32 v170, 16, v172
	v_and_b32_e32 v171, 0xffff0000, v172
	v_lshlrev_b32_e32 v172, 16, v173
	v_and_b32_e32 v173, 0xffff0000, v173
	v_lshlrev_b32_e32 v174, 16, v168
	v_and_b32_e32 v175, 0xffff0000, v168
	v_lshlrev_b32_e32 v168, 16, v169
	v_and_b32_e32 v169, 0xffff0000, v169
	v_pk_fma_f32 v[126:127], v[126:127], v[106:107], v[164:165]
	v_pk_fma_f32 v[124:125], v[124:125], v[104:105], v[166:167]
	v_pk_fma_f32 v[122:123], v[122:123], v[110:111], v[172:173]
	v_pk_fma_f32 v[120:121], v[120:121], v[108:109], v[170:171]
	v_lshlrev_b32_e32 v176, 16, v177
	v_and_b32_e32 v177, 0xffff0000, v177
	v_lshlrev_b32_e32 v178, 16, v179
	v_and_b32_e32 v179, 0xffff0000, v179
	v_pk_fma_f32 v[118:119], v[118:119], v[102:103], v[168:169]
	v_pk_fma_f32 v[116:117], v[116:117], v[100:101], v[174:175]
	v_mul_f32_e32 v164, v125, v125
	v_mul_f32_e32 v165, v127, v127
	v_mul_f32_e32 v166, v121, v121
	v_mul_f32_e32 v167, v123, v123
	v_pk_fma_f32 v[114:115], v[114:115], v[98:99], v[178:179]
	v_pk_fma_f32 v[112:113], v[112:113], v[96:97], v[176:177]
	v_mul_f32_e32 v168, v117, v117
	v_mul_f32_e32 v169, v119, v119
	v_fmac_f32_e32 v164, v124, v124
	v_fmac_f32_e32 v165, v126, v126
	v_fmac_f32_e32 v166, v120, v120
	v_fmac_f32_e32 v167, v122, v122
	v_mul_f32_e32 v170, v113, v113
	v_mul_f32_e32 v171, v115, v115
	v_fmac_f32_e32 v168, v116, v116
	v_fmac_f32_e32 v169, v118, v118
	v_add_f32_e32 v164, v164, v165
	v_add_f32_e32 v165, v166, v167
	v_fmac_f32_e32 v170, v112, v112
	v_fmac_f32_e32 v171, v114, v114
	v_add_f32_e32 v166, v168, v169
	v_add_f32_e32 v164, v164, v165
	v_add_f32_e32 v164, v164, v166
	v_add_f32_e32 v165, v170, v171
	v_add_f32_e32 v164, v165, v164
	v_mov_b32_e32 v219, v164
	v_mov_b32_e32 v165, v164
	s_nop 1
	v_permlane16_swap_b32_e32 v219, v165
	s_waitcnt lgkmcnt(0)
	v_add_f32_e32 v164, v164, v165
	v_mov_b32_e32 v219, v164
	v_mov_b32_e32 v165, v164
	s_nop 1
	v_permlane32_swap_b32_e32 v219, v165
	s_and_saveexec_b64 s[4:5], s[0:1]
	s_cbranch_execz .LBB0_1466
	s_waitcnt lgkmcnt(0)
	v_add_f32_e32 v164, v164, v165
	ds_write_b32 v189, v164 offset:256
.LBB0_1466:
	s_or_b64 exec, exec, s[4:5]
	v_or_b32_e32 v164, 32, v160
	s_waitcnt lgkmcnt(0)
	v_ashrrev_i32_e32 v165, 31, v164
	v_lshlrev_b64 v[166:167], 11, v[164:165]
	v_lshl_add_u64 v[166:167], s[74:75], 0, v[166:167]
	v_lshl_add_u64 v[166:167], v[158:159], 1, v[166:167]
	v_lshl_add_u64 v[170:171], v[166:167], 0, v[148:149]
	s_waitcnt vmcnt(10)
	v_mov_b64_e32 v[166:167], v[236:237]
	v_mov_b64_e32 v[168:169], v[238:239]
	s_nop 0
	v_mov_b64_e32 v[170:171], v[240:241]
	v_mov_b64_e32 v[172:173], v[242:243]
	s_nop 0
	v_mov_b32_e32 v174, v168
	v_mov_b32_e32 v175, v169
	s_nop 0
	v_mov_b32_e32 v179, v172
	v_mov_b32_e32 v193, v173
	v_permlane16_swap_b32_e32 v166, v174
	v_permlane16_swap_b32_e32 v167, v175
	v_permlane16_swap_b32_e32 v170, v179
	v_permlane16_swap_b32_e32 v171, v193
	v_lshlrev_b32_e32 v168, 16, v166
	v_and_b32_e32 v169, 0xffff0000, v166
	v_lshlrev_b32_e32 v166, 16, v167
	v_and_b32_e32 v167, 0xffff0000, v167
	v_lshlrev_b32_e32 v172, 16, v174
	v_and_b32_e32 v173, 0xffff0000, v174
	v_lshlrev_b32_e32 v174, 16, v175
	v_and_b32_e32 v175, 0xffff0000, v175
	v_lshlrev_b32_e32 v176, 16, v170
	v_and_b32_e32 v177, 0xffff0000, v170
	v_lshlrev_b32_e32 v170, 16, v171
	v_and_b32_e32 v171, 0xffff0000, v171
	v_pk_fma_f32 v[94:95], v[94:95], v[106:107], v[166:167]
	v_pk_fma_f32 v[92:93], v[92:93], v[104:105], v[168:169]
	v_pk_fma_f32 v[90:91], v[90:91], v[110:111], v[174:175]
	v_pk_fma_f32 v[88:89], v[88:89], v[108:109], v[172:173]
	v_lshlrev_b32_e32 v178, 16, v179
	v_and_b32_e32 v179, 0xffff0000, v179
	v_lshlrev_b32_e32 v194, 16, v193
	v_and_b32_e32 v195, 0xffff0000, v193
	v_pk_fma_f32 v[86:87], v[86:87], v[102:103], v[170:171]
	v_pk_fma_f32 v[84:85], v[84:85], v[100:101], v[176:177]
	v_mul_f32_e32 v166, v93, v93
	v_mul_f32_e32 v167, v95, v95
	v_mul_f32_e32 v168, v89, v89
	v_mul_f32_e32 v169, v91, v91
	v_pk_fma_f32 v[82:83], v[82:83], v[98:99], v[194:195]
	v_pk_fma_f32 v[80:81], v[80:81], v[96:97], v[178:179]
	v_mul_f32_e32 v170, v85, v85
	v_mul_f32_e32 v171, v87, v87
	v_fmac_f32_e32 v166, v92, v92
	v_fmac_f32_e32 v167, v94, v94
	v_fmac_f32_e32 v168, v88, v88
	v_fmac_f32_e32 v169, v90, v90
	v_mul_f32_e32 v172, v81, v81
	v_mul_f32_e32 v173, v83, v83
	v_fmac_f32_e32 v170, v84, v84
	v_fmac_f32_e32 v171, v86, v86
	v_add_f32_e32 v166, v166, v167
	v_add_f32_e32 v167, v168, v169
	v_fmac_f32_e32 v172, v80, v80
	v_fmac_f32_e32 v173, v82, v82
	v_add_f32_e32 v168, v170, v171
	v_add_f32_e32 v166, v166, v167
	v_add_f32_e32 v166, v166, v168
	v_add_f32_e32 v167, v172, v173
	v_add_f32_e32 v166, v167, v166
	v_mov_b32_e32 v219, v166
	v_mov_b32_e32 v167, v166
	s_nop 1
	v_permlane16_swap_b32_e32 v219, v167
	s_waitcnt lgkmcnt(0)
	v_add_f32_e32 v166, v166, v167
	v_mov_b32_e32 v219, v166
	v_mov_b32_e32 v167, v166
	s_nop 1
	v_permlane32_swap_b32_e32 v219, v167
	s_and_saveexec_b64 s[4:5], s[0:1]
	s_cbranch_execz .LBB0_1468
	s_waitcnt lgkmcnt(0)
	v_add_f32_e32 v166, v166, v167
	ds_write_b32 v189, v166 offset:512
.LBB0_1468:
	s_or_b64 exec, exec, s[4:5]
	v_or_b32_e32 v166, 48, v160
	s_waitcnt lgkmcnt(0)
	v_ashrrev_i32_e32 v167, 31, v166
	v_lshlrev_b64 v[168:169], 11, v[166:167]
	v_lshl_add_u64 v[168:169], s[74:75], 0, v[168:169]
	v_lshl_add_u64 v[168:169], v[158:159], 1, v[168:169]
	v_lshl_add_u64 v[172:173], v[168:169], 0, v[148:149]
	s_waitcnt vmcnt(8)
	v_mov_b64_e32 v[168:169], v[244:245]
	v_mov_b64_e32 v[170:171], v[246:247]
	s_nop 0
	v_mov_b64_e32 v[172:173], v[248:249]
	v_mov_b64_e32 v[174:175], v[250:251]
	s_nop 0
	v_mov_b32_e32 v176, v170
	v_mov_b32_e32 v177, v171
	s_nop 0
	v_mov_b32_e32 v193, v174
	v_mov_b32_e32 v197, v175
	v_permlane16_swap_b32_e32 v168, v176
	v_permlane16_swap_b32_e32 v169, v177
	v_permlane16_swap_b32_e32 v172, v193
	v_permlane16_swap_b32_e32 v173, v197
	v_lshlrev_b32_e32 v170, 16, v168
	v_and_b32_e32 v171, 0xffff0000, v168
	v_lshlrev_b32_e32 v168, 16, v169
	v_and_b32_e32 v169, 0xffff0000, v169
	v_lshlrev_b32_e32 v174, 16, v176
	v_and_b32_e32 v175, 0xffff0000, v176
	v_lshlrev_b32_e32 v176, 16, v177
	v_and_b32_e32 v177, 0xffff0000, v177
	v_lshlrev_b32_e32 v178, 16, v172
	v_and_b32_e32 v179, 0xffff0000, v172
	v_lshlrev_b32_e32 v172, 16, v173
	v_and_b32_e32 v173, 0xffff0000, v173
	v_pk_fma_f32 v[168:169], v[78:79], v[106:107], v[168:169]
	v_pk_fma_f32 v[76:77], v[76:77], v[104:105], v[170:171]
	v_pk_fma_f32 v[74:75], v[74:75], v[110:111], v[176:177]
	v_pk_fma_f32 v[72:73], v[72:73], v[108:109], v[174:175]
	v_lshlrev_b32_e32 v194, 16, v193
	v_and_b32_e32 v195, 0xffff0000, v193
	v_lshlrev_b32_e32 v196, 16, v197
	v_and_b32_e32 v197, 0xffff0000, v197
	v_pk_fma_f32 v[70:71], v[70:71], v[102:103], v[172:173]
	v_pk_fma_f32 v[68:69], v[68:69], v[100:101], v[178:179]
	v_mul_f32_e32 v78, v77, v77
	v_mul_f32_e32 v79, v169, v169
	v_mul_f32_e32 v170, v73, v73
	v_mul_f32_e32 v171, v75, v75
	v_pk_fma_f32 v[66:67], v[66:67], v[98:99], v[196:197]
	v_pk_fma_f32 v[64:65], v[64:65], v[96:97], v[194:195]
	v_mul_f32_e32 v172, v69, v69
	v_mul_f32_e32 v173, v71, v71
	v_fmac_f32_e32 v78, v76, v76
	v_fmac_f32_e32 v79, v168, v168
	v_fmac_f32_e32 v170, v72, v72
	v_fmac_f32_e32 v171, v74, v74
	v_mul_f32_e32 v174, v65, v65
	v_mul_f32_e32 v175, v67, v67
	v_fmac_f32_e32 v172, v68, v68
	v_fmac_f32_e32 v173, v70, v70
	v_add_f32_e32 v78, v78, v79
	v_add_f32_e32 v79, v170, v171
	v_fmac_f32_e32 v174, v64, v64
	v_fmac_f32_e32 v175, v66, v66
	v_add_f32_e32 v170, v172, v173
	v_add_f32_e32 v78, v78, v79
	v_add_f32_e32 v78, v78, v170
	v_add_f32_e32 v79, v174, v175
	v_add_f32_e32 v78, v79, v78
	v_mov_b32_e32 v219, v78
	v_mov_b32_e32 v79, v78
	s_nop 1
	v_permlane16_swap_b32_e32 v219, v79
	s_waitcnt lgkmcnt(0)
	v_add_f32_e32 v78, v78, v79
	v_mov_b32_e32 v219, v78
	v_mov_b32_e32 v79, v78
	s_nop 1
	v_permlane32_swap_b32_e32 v219, v79
	s_and_saveexec_b64 s[4:5], s[0:1]
	s_cbranch_execz .LBB0_1470
	s_waitcnt lgkmcnt(0)
	v_add_f32_e32 v78, v78, v79
	ds_write_b32 v189, v78 offset:768
.LBB0_1470:
	s_or_b64 exec, exec, s[4:5]
	v_add_u32_e32 v78, 0x80, v160
	s_waitcnt lgkmcnt(0)
	v_ashrrev_i32_e32 v79, 31, v78
	v_lshlrev_b64 v[170:171], 11, v[78:79]
	v_lshl_add_u64 v[170:171], s[74:75], 0, v[170:171]
	v_lshl_add_u64 v[170:171], v[158:159], 1, v[170:171]
	v_lshl_add_u64 v[174:175], v[170:171], 0, v[148:149]
	s_waitcnt vmcnt(6)
	v_mov_b64_e32 v[170:171], v[252:253]
	v_mov_b64_e32 v[172:173], v[254:255]
	s_nop 0
	v_mov_b64_e32 v[174:175], v[144:145]
	v_mov_b64_e32 v[176:177], v[146:147]
	s_nop 0
	v_mov_b32_e32 v178, v172
	v_mov_b32_e32 v179, v173
	s_nop 0
	v_mov_b32_e32 v193, v176
	v_mov_b32_e32 v199, v177
	v_permlane16_swap_b32_e32 v170, v178
	v_permlane16_swap_b32_e32 v171, v179
	v_permlane16_swap_b32_e32 v174, v193
	v_permlane16_swap_b32_e32 v175, v199
	v_lshlrev_b32_e32 v172, 16, v170
	v_and_b32_e32 v173, 0xffff0000, v170
	v_lshlrev_b32_e32 v170, 16, v171
	v_and_b32_e32 v171, 0xffff0000, v171
	v_lshlrev_b32_e32 v176, 16, v178
	v_and_b32_e32 v177, 0xffff0000, v178
	v_lshlrev_b32_e32 v178, 16, v179
	v_and_b32_e32 v179, 0xffff0000, v179
	v_lshlrev_b32_e32 v194, 16, v174
	v_and_b32_e32 v195, 0xffff0000, v174
	v_lshlrev_b32_e32 v174, 16, v175
	v_and_b32_e32 v175, 0xffff0000, v175
	v_pk_fma_f32 v[62:63], v[62:63], v[106:107], v[170:171]
	v_pk_fma_f32 v[60:61], v[60:61], v[104:105], v[172:173]
	v_pk_fma_f32 v[58:59], v[58:59], v[110:111], v[178:179]
	v_pk_fma_f32 v[56:57], v[56:57], v[108:109], v[176:177]
	v_lshlrev_b32_e32 v196, 16, v193
	v_and_b32_e32 v197, 0xffff0000, v193
	v_lshlrev_b32_e32 v198, 16, v199
	v_and_b32_e32 v199, 0xffff0000, v199
	v_pk_fma_f32 v[54:55], v[54:55], v[102:103], v[174:175]
	v_pk_fma_f32 v[52:53], v[52:53], v[100:101], v[194:195]
	v_mul_f32_e32 v170, v61, v61
	v_mul_f32_e32 v171, v63, v63
	v_mul_f32_e32 v172, v57, v57
	v_mul_f32_e32 v173, v59, v59
	v_pk_fma_f32 v[50:51], v[50:51], v[98:99], v[198:199]
	v_pk_fma_f32 v[48:49], v[48:49], v[96:97], v[196:197]
	v_mul_f32_e32 v174, v53, v53
	v_mul_f32_e32 v175, v55, v55
	v_fmac_f32_e32 v170, v60, v60
	v_fmac_f32_e32 v171, v62, v62
	v_fmac_f32_e32 v172, v56, v56
	v_fmac_f32_e32 v173, v58, v58
	v_mul_f32_e32 v176, v49, v49
	v_mul_f32_e32 v177, v51, v51
	v_fmac_f32_e32 v174, v52, v52
	v_fmac_f32_e32 v175, v54, v54
	v_add_f32_e32 v170, v170, v171
	v_add_f32_e32 v171, v172, v173
	v_fmac_f32_e32 v176, v48, v48
	v_fmac_f32_e32 v177, v50, v50
	v_add_f32_e32 v172, v174, v175
	v_add_f32_e32 v170, v170, v171
	v_add_f32_e32 v170, v170, v172
	v_add_f32_e32 v171, v176, v177
	v_add_f32_e32 v170, v171, v170
	v_mov_b32_e32 v219, v170
	v_mov_b32_e32 v171, v170
	s_nop 1
	v_permlane16_swap_b32_e32 v219, v171
	s_waitcnt lgkmcnt(0)
	v_add_f32_e32 v170, v170, v171
	v_mov_b32_e32 v219, v170
	v_mov_b32_e32 v171, v170
	s_nop 1
	v_permlane32_swap_b32_e32 v219, v171
	s_and_saveexec_b64 s[4:5], s[0:1]
	s_cbranch_execz .LBB0_1472
	s_waitcnt lgkmcnt(0)
	v_add_f32_e32 v170, v170, v171
	ds_write_b32 v189, v170 offset:2048
.LBB0_1472:
	s_or_b64 exec, exec, s[4:5]
	v_add_u32_e32 v170, 0x90, v160
	s_waitcnt lgkmcnt(0)
	v_ashrrev_i32_e32 v171, 31, v170
	v_lshlrev_b64 v[172:173], 11, v[170:171]
	v_lshl_add_u64 v[172:173], s[74:75], 0, v[172:173]
	v_lshl_add_u64 v[172:173], v[158:159], 1, v[172:173]
	v_lshl_add_u64 v[176:177], v[172:173], 0, v[148:149]
	s_waitcnt vmcnt(4)
	v_mov_b64_e32 v[172:173], v[150:151]
	v_mov_b64_e32 v[174:175], v[152:153]
	s_nop 0
	v_mov_b64_e32 v[176:177], v[154:155]
	v_mov_b64_e32 v[178:179], v[156:157]
	s_nop 0
	v_mov_b32_e32 v193, v174
	v_mov_b32_e32 v195, v175
	s_nop 0
	v_mov_b32_e32 v199, v178
	v_mov_b32_e32 v201, v179
	v_permlane16_swap_b32_e32 v172, v193
	v_permlane16_swap_b32_e32 v173, v195
	v_permlane16_swap_b32_e32 v176, v199
	v_permlane16_swap_b32_e32 v177, v201
	v_lshlrev_b32_e32 v174, 16, v172
	v_and_b32_e32 v175, 0xffff0000, v172
	v_lshlrev_b32_e32 v172, 16, v173
	v_and_b32_e32 v173, 0xffff0000, v173
	v_lshlrev_b32_e32 v178, 16, v193
	v_and_b32_e32 v179, 0xffff0000, v193
	v_lshlrev_b32_e32 v194, 16, v195
	v_and_b32_e32 v195, 0xffff0000, v195
	v_lshlrev_b32_e32 v196, 16, v176
	v_and_b32_e32 v197, 0xffff0000, v176
	v_lshlrev_b32_e32 v176, 16, v177
	v_and_b32_e32 v177, 0xffff0000, v177
	v_pk_fma_f32 v[46:47], v[46:47], v[106:107], v[172:173]
	v_pk_fma_f32 v[44:45], v[44:45], v[104:105], v[174:175]
	v_pk_fma_f32 v[42:43], v[42:43], v[110:111], v[194:195]
	v_pk_fma_f32 v[40:41], v[40:41], v[108:109], v[178:179]
	v_lshlrev_b32_e32 v198, 16, v199
	v_and_b32_e32 v199, 0xffff0000, v199
	v_lshlrev_b32_e32 v200, 16, v201
	v_and_b32_e32 v201, 0xffff0000, v201
	v_pk_fma_f32 v[38:39], v[38:39], v[102:103], v[176:177]
	v_pk_fma_f32 v[36:37], v[36:37], v[100:101], v[196:197]
	v_mul_f32_e32 v172, v45, v45
	v_mul_f32_e32 v173, v47, v47
	v_mul_f32_e32 v174, v41, v41
	v_mul_f32_e32 v175, v43, v43
	v_pk_fma_f32 v[34:35], v[34:35], v[98:99], v[200:201]
	v_pk_fma_f32 v[32:33], v[32:33], v[96:97], v[198:199]
	v_mul_f32_e32 v176, v37, v37
	v_mul_f32_e32 v177, v39, v39
	v_fmac_f32_e32 v172, v44, v44
	v_fmac_f32_e32 v173, v46, v46
	v_fmac_f32_e32 v174, v40, v40
	v_fmac_f32_e32 v175, v42, v42
	v_mul_f32_e32 v178, v33, v33
	v_mul_f32_e32 v179, v35, v35
	v_fmac_f32_e32 v176, v36, v36
	v_fmac_f32_e32 v177, v38, v38
	v_add_f32_e32 v172, v172, v173
	v_add_f32_e32 v173, v174, v175
	v_fmac_f32_e32 v178, v32, v32
	v_fmac_f32_e32 v179, v34, v34
	v_add_f32_e32 v174, v176, v177
	v_add_f32_e32 v172, v172, v173
	v_add_f32_e32 v172, v172, v174
	v_add_f32_e32 v173, v178, v179
	v_add_f32_e32 v172, v173, v172
	v_mov_b32_e32 v219, v172
	v_mov_b32_e32 v173, v172
	s_nop 1
	v_permlane16_swap_b32_e32 v219, v173
	s_waitcnt lgkmcnt(0)
	v_add_f32_e32 v172, v172, v173
	v_mov_b32_e32 v219, v172
	v_mov_b32_e32 v173, v172
	s_nop 1
	v_permlane32_swap_b32_e32 v219, v173
	s_and_saveexec_b64 s[4:5], s[0:1]
	s_cbranch_execz .LBB0_1474
	s_waitcnt lgkmcnt(0)
	v_add_f32_e32 v172, v172, v173
	ds_write_b32 v189, v172 offset:2304
.LBB0_1474:
	s_or_b64 exec, exec, s[4:5]
	v_add_u32_e32 v172, 0xa0, v160
	s_waitcnt lgkmcnt(0)
	v_ashrrev_i32_e32 v173, 31, v172
	v_lshlrev_b64 v[174:175], 11, v[172:173]
	v_lshl_add_u64 v[174:175], s[74:75], 0, v[174:175]
	v_lshl_add_u64 v[174:175], v[158:159], 1, v[174:175]
	v_lshl_add_u64 v[178:179], v[174:175], 0, v[148:149]
	s_waitcnt vmcnt(2)
	v_mov_b64_e32 v[174:175], v[210:211]
	v_mov_b64_e32 v[176:177], v[212:213]
	v_mov_b64_e32 v[194:195], v[214:215]
	v_mov_b64_e32 v[196:197], v[216:217]
	s_nop 0
	v_mov_b32_e32 v179, v176
	v_mov_b32_e32 v193, v177
	s_nop 0
	v_mov_b32_e32 v201, v196
	v_mov_b32_e32 v203, v197
	v_permlane16_swap_b32_e32 v174, v179
	v_permlane16_swap_b32_e32 v175, v193
	v_permlane16_swap_b32_e32 v194, v201
	v_permlane16_swap_b32_e32 v195, v203
	v_lshlrev_b32_e32 v176, 16, v174
	v_and_b32_e32 v177, 0xffff0000, v174
	v_lshlrev_b32_e32 v174, 16, v175
	v_and_b32_e32 v175, 0xffff0000, v175
	v_lshlrev_b32_e32 v178, 16, v179
	v_and_b32_e32 v179, 0xffff0000, v179
	v_lshlrev_b32_e32 v196, 16, v193
	v_and_b32_e32 v197, 0xffff0000, v193
	v_lshlrev_b32_e32 v198, 16, v194
	v_and_b32_e32 v199, 0xffff0000, v194
	v_lshlrev_b32_e32 v194, 16, v195
	v_and_b32_e32 v195, 0xffff0000, v195
	v_pk_fma_f32 v[30:31], v[30:31], v[106:107], v[174:175]
	v_pk_fma_f32 v[28:29], v[28:29], v[104:105], v[176:177]
	v_pk_fma_f32 v[26:27], v[26:27], v[110:111], v[196:197]
	v_pk_fma_f32 v[24:25], v[24:25], v[108:109], v[178:179]
	v_lshlrev_b32_e32 v200, 16, v201
	v_and_b32_e32 v201, 0xffff0000, v201
	v_lshlrev_b32_e32 v202, 16, v203
	v_and_b32_e32 v203, 0xffff0000, v203
	v_pk_fma_f32 v[22:23], v[22:23], v[102:103], v[194:195]
	v_pk_fma_f32 v[20:21], v[20:21], v[100:101], v[198:199]
	v_mul_f32_e32 v174, v29, v29
	v_mul_f32_e32 v175, v31, v31
	v_mul_f32_e32 v176, v25, v25
	v_mul_f32_e32 v177, v27, v27
	v_pk_fma_f32 v[18:19], v[18:19], v[98:99], v[202:203]
	v_pk_fma_f32 v[16:17], v[16:17], v[96:97], v[200:201]
	v_mul_f32_e32 v178, v21, v21
	v_mul_f32_e32 v179, v23, v23
	v_fmac_f32_e32 v174, v28, v28
	v_fmac_f32_e32 v175, v30, v30
	v_fmac_f32_e32 v176, v24, v24
	v_fmac_f32_e32 v177, v26, v26
	v_mul_f32_e32 v193, v17, v17
	v_mul_f32_e32 v194, v19, v19
	v_fmac_f32_e32 v178, v20, v20
	v_fmac_f32_e32 v179, v22, v22
	v_add_f32_e32 v174, v174, v175
	v_add_f32_e32 v175, v176, v177
	v_fmac_f32_e32 v193, v16, v16
	v_fmac_f32_e32 v194, v18, v18
	v_add_f32_e32 v176, v178, v179
	v_add_f32_e32 v174, v174, v175
	v_add_f32_e32 v174, v174, v176
	v_add_f32_e32 v175, v193, v194
	v_add_f32_e32 v174, v175, v174
	v_mov_b32_e32 v219, v174
	v_mov_b32_e32 v175, v174
	s_nop 1
	v_permlane16_swap_b32_e32 v219, v175
	s_waitcnt lgkmcnt(0)
	v_add_f32_e32 v174, v174, v175
	v_mov_b32_e32 v219, v174
	v_mov_b32_e32 v175, v174
	s_nop 1
	v_permlane32_swap_b32_e32 v219, v175
	s_and_saveexec_b64 s[4:5], s[0:1]
	s_cbranch_execz .LBB0_1476
	s_waitcnt lgkmcnt(0)
	v_add_f32_e32 v174, v174, v175
	ds_write_b32 v189, v174 offset:2560
.LBB0_1476:
	s_or_b64 exec, exec, s[4:5]
	v_add_u32_e32 v174, 0xb0, v160
	s_waitcnt lgkmcnt(0)
	v_ashrrev_i32_e32 v175, 31, v174
	v_lshlrev_b64 v[176:177], 11, v[174:175]
	v_lshl_add_u64 v[176:177], s[74:75], 0, v[176:177]
	v_lshl_add_u64 v[176:177], v[158:159], 1, v[176:177]
	v_lshl_add_u64 v[194:195], v[176:177], 0, v[148:149]
	s_waitcnt vmcnt(0)
	v_mov_b64_e32 v[176:177], v[220:221]
	v_mov_b64_e32 v[178:179], v[222:223]
	s_nop 0
	v_mov_b64_e32 v[194:195], v[224:225]
	v_mov_b64_e32 v[196:197], v[226:227]
	s_nop 0
	v_mov_b32_e32 v193, v178
	v_mov_b32_e32 v199, v179
	s_nop 0
	v_mov_b32_e32 v203, v196
	v_mov_b32_e32 v205, v197
	v_permlane16_swap_b32_e32 v176, v193
	v_permlane16_swap_b32_e32 v177, v199
	v_permlane16_swap_b32_e32 v194, v203
	v_permlane16_swap_b32_e32 v195, v205
	v_lshlrev_b32_e32 v178, 16, v176
	v_and_b32_e32 v179, 0xffff0000, v176
	v_lshlrev_b32_e32 v176, 16, v177
	v_and_b32_e32 v177, 0xffff0000, v177
	v_lshlrev_b32_e32 v196, 16, v193
	v_and_b32_e32 v197, 0xffff0000, v193
	v_lshlrev_b32_e32 v198, 16, v199
	v_and_b32_e32 v199, 0xffff0000, v199
	v_lshlrev_b32_e32 v200, 16, v194
	v_and_b32_e32 v201, 0xffff0000, v194
	v_lshlrev_b32_e32 v194, 16, v195
	v_and_b32_e32 v195, 0xffff0000, v195
	v_lshlrev_b32_e32 v202, 16, v203
	v_and_b32_e32 v203, 0xffff0000, v203
	v_lshlrev_b32_e32 v204, 16, v205
	v_and_b32_e32 v205, 0xffff0000, v205
	v_pk_fma_f32 v[176:177], v[14:15], v[106:107], v[176:177]
	v_pk_fma_f32 v[178:179], v[12:13], v[104:105], v[178:179]
	v_pk_fma_f32 v[104:105], v[10:11], v[110:111], v[198:199]
	v_pk_fma_f32 v[106:107], v[8:9], v[108:109], v[196:197]
	v_pk_fma_f32 v[102:103], v[6:7], v[102:103], v[194:195]
	v_pk_fma_f32 v[100:101], v[4:5], v[100:101], v[200:201]
	v_pk_fma_f32 v[98:99], v[2:3], v[98:99], v[204:205]
	v_pk_fma_f32 v[96:97], v[0:1], v[96:97], v[202:203]
	v_mul_f32_e32 v0, v179, v179
	v_mul_f32_e32 v1, v177, v177
	v_mul_f32_e32 v2, v107, v107
	v_mul_f32_e32 v3, v105, v105
	v_mul_f32_e32 v4, v101, v101
	v_mul_f32_e32 v5, v103, v103
	v_fmac_f32_e32 v0, v178, v178
	v_fmac_f32_e32 v1, v176, v176
	v_fmac_f32_e32 v2, v106, v106
	v_fmac_f32_e32 v3, v104, v104
	v_mul_f32_e32 v6, v97, v97
	v_mul_f32_e32 v7, v99, v99
	v_fmac_f32_e32 v4, v100, v100
	v_fmac_f32_e32 v5, v102, v102
	v_add_f32_e32 v0, v0, v1
	v_add_f32_e32 v1, v2, v3
	v_fmac_f32_e32 v6, v96, v96
	v_fmac_f32_e32 v7, v98, v98
	v_add_f32_e32 v2, v4, v5
	v_add_f32_e32 v0, v0, v1
	v_add_f32_e32 v0, v0, v2
	v_add_f32_e32 v1, v6, v7
	v_add_f32_e32 v0, v1, v0
	v_mov_b32_e32 v219, v0
	v_mov_b32_e32 v1, v0
	s_nop 1
	v_permlane16_swap_b32_e32 v219, v1
	s_waitcnt lgkmcnt(0)
	v_add_f32_e32 v0, v0, v1
	v_mov_b32_e32 v219, v0
	v_mov_b32_e32 v1, v0
	s_nop 1
	v_permlane32_swap_b32_e32 v219, v1
	s_and_saveexec_b64 s[4:5], s[0:1]
	s_cbranch_execz .LBB0_1478
	s_waitcnt lgkmcnt(0)
	v_add_f32_e32 v0, v0, v1
	ds_write_b32 v189, v0 offset:2816
